# sc1 write-through on all 8-byte stores
# baseline (speedup 1.0000x reference)
.LBB0_49:
	v_lshrrev_b32_e32 v1, 3, v2
	v_and_b32_e32 v0, 0x700, v80
	v_and_b32_e32 v1, 0xf8, v1
	v_and_b32_e32 v3, 0xfffff807, v2
	v_or3_b32 v0, v0, v3, v1
	v_cndmask_b32_e32 v0, v2, v0, vcc
	v_ashrrev_i32_e32 v1, 31, v0
	v_lshlrev_b64 v[4:5], 12, v[0:1]
	v_lshl_add_u64 v[4:5], v[66:67], 0, v[4:5]
	s_waitcnt lgkmcnt(0)
	global_load_dwordx4 v[48:51], v[4:5], off
	global_load_dwordx4 v[52:55], v[4:5], off offset:1024
	global_load_dwordx4 v[56:59], v[4:5], off offset:2048
	global_load_dwordx4 v[60:63], v[4:5], off offset:3072
	v_add_u32_e32 v3, s18, v2
	v_cmp_gt_i32_e64 s[6:7], s3, v3
	v_lshlrev_b64 v[0:1], 11, v[0:1]
	s_waitcnt vmcnt(1)
	v_mov_b32_e32 v84, v57
	v_cndmask_b32_e64 v4, v2, v3, s[6:7]
	v_lshlrev_b32_e32 v5, 5, v4
	v_lshrrev_b32_e32 v6, 3, v4
	v_and_b32_e32 v7, 0xfffff807, v4
	v_and_b32_e32 v5, 0x700, v5
	v_and_b32_e32 v6, 0xf8, v6
	v_or3_b32 v5, v5, v7, v6
	v_cndmask_b32_e32 v72, v4, v5, vcc
	v_ashrrev_i32_e32 v73, 31, v72
	v_lshlrev_b64 v[4:5], 12, v[72:73]
	v_lshl_add_u64 v[4:5], v[66:67], 0, v[4:5]
	global_load_dwordx4 v[16:19], v[4:5], off offset:1024
	global_load_dwordx4 v[32:35], v[4:5], off
	global_load_dwordx4 v[20:23], v[4:5], off offset:2048
	v_add_u32_e32 v3, s18, v3
	v_cmp_gt_i32_e64 s[8:9], s3, v3
	global_load_dwordx4 v[12:15], v[4:5], off offset:3072
	v_add_u32_e32 v82, s18, v3
	v_cndmask_b32_e64 v4, v2, v3, s[8:9]
	v_lshlrev_b32_e32 v3, 5, v4
	v_lshrrev_b32_e32 v5, 3, v4
	v_cmp_gt_i32_e64 s[4:5], s3, v82
	v_and_b32_e32 v6, 0xfffff807, v4
	v_and_b32_e32 v3, 0x700, v3
	v_cndmask_b32_e64 v2, v2, v82, s[4:5]
	v_and_b32_e32 v5, 0xf8, v5
	v_lshlrev_b32_e32 v7, 5, v2
	v_lshrrev_b32_e32 v8, 3, v2
	v_or3_b32 v3, v3, v6, v5
	v_and_b32_e32 v9, 0xfffff807, v2
	v_and_b32_e32 v5, 0x700, v7
	v_and_b32_e32 v6, 0xf8, v8
	v_cndmask_b32_e32 v70, v4, v3, vcc
	v_or3_b32 v3, v5, v9, v6
	v_ashrrev_i32_e32 v71, 31, v70
	v_cndmask_b32_e32 v68, v2, v3, vcc
	v_lshlrev_b64 v[2:3], 12, v[70:71]
	v_mov_b32_e32 v8, v49
	v_mov_b32_e32 v9, v53
	v_lshl_add_u64 v[2:3], v[66:67], 0, v[2:3]
	v_mov_b32_e32 v6, v48
	v_mov_b32_e32 v7, v52
	s_waitcnt vmcnt(4)
	v_mov_b32_e32 v85, v61
	v_pk_mul_f32 v[8:9], v[8:9], v[8:9]
	global_load_dwordx4 v[44:47], v[2:3], off
	global_load_dwordx4 v[36:39], v[2:3], off offset:1024
	global_load_dwordx4 v[40:43], v[2:3], off offset:2048
	global_load_dwordx4 v[28:31], v[2:3], off offset:3072
	v_mov_b32_e32 v2, v50
	v_mov_b32_e32 v3, v54
	v_mov_b32_e32 v26, v56
	v_mov_b32_e32 v27, v60
	v_pk_mul_f32 v[84:85], v[84:85], v[84:85]
	v_pk_fma_f32 v[6:7], v[6:7], v[6:7], v[8:9]
	v_mov_b32_e32 v4, v51
	v_mov_b32_e32 v5, v55
	v_mov_b32_e32 v10, v58
	v_mov_b32_e32 v11, v62
	v_pk_fma_f32 v[8:9], v[26:27], v[26:27], v[84:85]
	v_pk_fma_f32 v[2:3], v[2:3], v[2:3], v[6:7]
	v_mov_b32_e32 v24, v59
	v_mov_b32_e32 v25, v63
	v_pk_fma_f32 v[6:7], v[10:11], v[10:11], v[8:9]
	v_pk_fma_f32 v[2:3], v[4:5], v[4:5], v[2:3]
	v_pk_fma_f32 v[4:5], v[24:25], v[24:25], v[6:7]
	v_add_f32_e32 v2, v2, v3
	v_add_f32_e32 v2, v2, v4
	v_add_f32_e32 v8, v2, v5
	ds_bpermute_b32 v9, v74, v8
	v_ashrrev_i32_e32 v69, 31, v68
	v_lshlrev_b64 v[2:3], 12, v[68:69]
	v_lshl_add_u64 v[2:3], v[66:67], 0, v[2:3]
	global_load_dwordx4 v[4:7], v[2:3], off offset:1024
	global_load_dwordx4 v[24:27], v[2:3], off
	s_waitcnt lgkmcnt(0)
	v_add_f32_e32 v8, v8, v9
	ds_bpermute_b32 v9, v75, v8
	v_lshl_add_u64 v[84:85], v[64:65], 0, v[0:1]
	s_waitcnt lgkmcnt(0)
	v_add_f32_e32 v83, v8, v9
	global_load_dwordx4 v[8:11], v[2:3], off offset:2048
	s_nop 0
	global_load_dwordx4 v[0:3], v[2:3], off offset:3072
	ds_bpermute_b32 v88, v76, v83
	s_waitcnt lgkmcnt(0)
	v_add_f32_e32 v83, v83, v88
	ds_bpermute_b32 v96, v77, v83
	s_waitcnt lgkmcnt(0)
	v_add_f32_e32 v83, v83, v96
	ds_bpermute_b32 v100, v78, v83
	s_waitcnt vmcnt(11)
	v_pk_mul_f32 v[86:87], v[16:17], v[16:17]
	s_waitcnt vmcnt(10)
	v_pk_mul_f32 v[90:91], v[32:33], v[32:33]
	v_add_f32_e32 v86, v86, v87
	v_add_f32_e32 v87, v90, v91
	s_waitcnt lgkmcnt(0)
	v_add_f32_e32 v83, v83, v100
	ds_bpermute_b32 v90, v79, v83
	v_pk_mul_f32 v[88:89], v[18:19], v[18:19]
	v_pk_mul_f32 v[92:93], v[34:35], v[34:35]
	v_add_f32_e32 v86, v86, v88
	s_waitcnt vmcnt(9)
	v_pk_mul_f32 v[94:95], v[20:21], v[20:21]
	s_waitcnt lgkmcnt(0)
	v_add_f32_e32 v83, v83, v90
	v_fmamk_f32 v83, v83, 0x3a800000, v81
	v_mul_f32_e32 v90, 0x4b800000, v83
	v_cmp_gt_f32_e64 s[10:11], s22, v83
	v_add_f32_e32 v87, v87, v92
	v_pk_mul_f32 v[96:97], v[22:23], v[22:23]
	v_cndmask_b32_e64 v83, v83, v90, s[10:11]
	v_rsq_f32_e32 v83, v83
	v_add_f32_e32 v90, v86, v89
	s_waitcnt vmcnt(8)
	v_pk_mul_f32 v[98:99], v[12:13], v[12:13]
	v_add_f32_e32 v91, v94, v95
	v_mul_f32_e32 v86, 0x45800000, v83
	v_cndmask_b32_e64 v86, v83, v86, s[10:11]
	v_pk_mul_f32 v[48:49], v[48:49], v[86:87] op_sel_hi:[1,0]
	v_pk_mul_f32 v[50:51], v[50:51], v[86:87] op_sel_hi:[1,0]
	v_add_f32_e32 v88, v91, v96
	v_add_f32_e32 v91, v87, v93
	v_pk_mul_f32 v[52:53], v[52:53], v[86:87] op_sel_hi:[1,0]
	v_pk_mul_f32 v[54:55], v[54:55], v[86:87] op_sel_hi:[1,0]
	v_pk_mul_f32 v[56:57], v[56:57], v[86:87] op_sel_hi:[1,0]
	v_pk_mul_f32 v[58:59], v[58:59], v[86:87] op_sel_hi:[1,0]
	v_pk_mul_f32 v[60:61], v[60:61], v[86:87] op_sel_hi:[1,0]
	v_pk_mul_f32 v[62:63], v[62:63], v[86:87] op_sel_hi:[1,0]
	v_cvt_pk_bf16_f32 v86, v48, v49
	v_cvt_pk_bf16_f32 v87, v50, v51
	v_add_f32_e32 v50, v98, v99
	v_pk_mul_f32 v[48:49], v[14:15], v[14:15]
	v_add_f32_e32 v92, v88, v97
	v_add_f32_e32 v48, v50, v48
	v_add_f32_e32 v50, v48, v49
	s_waitcnt vmcnt(6)
	v_pk_mul_f32 v[48:49], v[36:37], v[36:37]
	v_cvt_pk_bf16_f32 v88, v52, v53
	v_add_f32_e32 v51, v48, v49
	v_pk_mul_f32 v[48:49], v[38:39], v[38:39]
	v_cvt_pk_bf16_f32 v89, v54, v55
	v_add_f32_e32 v48, v51, v48
	v_add_f32_e32 v51, v48, v49
	v_pk_mul_f32 v[48:49], v[44:45], v[44:45]
	v_cvt_pk_bf16_f32 v54, v56, v57
	v_add_f32_e32 v52, v48, v49
	v_pk_mul_f32 v[48:49], v[46:47], v[46:47]
	v_cvt_pk_bf16_f32 v55, v58, v59
	v_add_f32_e32 v48, v52, v48
	v_add_f32_e32 v52, v48, v49
	s_waitcnt vmcnt(5)
	v_pk_mul_f32 v[48:49], v[40:41], v[40:41]
	s_nop 0
	v_add_f32_e32 v53, v48, v49
	v_pk_mul_f32 v[48:49], v[42:43], v[42:43]
	s_nop 0
	v_add_f32_e32 v48, v53, v48
	v_add_f32_e32 v53, v48, v49
	s_waitcnt vmcnt(4)
	v_pk_mul_f32 v[48:49], v[28:29], v[28:29]
	s_nop 0
	v_add_f32_e32 v56, v48, v49
	v_pk_mul_f32 v[48:49], v[30:31], v[30:31]
	s_nop 0
	v_add_f32_e32 v48, v56, v48
	v_add_f32_e32 v56, v48, v49
	s_waitcnt vmcnt(3)
	v_pk_mul_f32 v[48:49], v[4:5], v[4:5]
	s_nop 0
	v_add_f32_e32 v57, v48, v49
	v_pk_mul_f32 v[48:49], v[6:7], v[6:7]
	s_nop 0
	v_add_f32_e32 v48, v57, v48
	v_add_f32_e32 v57, v48, v49
	s_waitcnt vmcnt(2)
	v_pk_mul_f32 v[48:49], v[24:25], v[24:25]
	s_nop 0
	v_add_f32_e32 v58, v48, v49
	v_pk_mul_f32 v[48:49], v[26:27], v[26:27]
	s_nop 0
	v_add_f32_e32 v48, v58, v48
	v_add_f32_e32 v58, v48, v49
	s_waitcnt vmcnt(1)
	v_pk_mul_f32 v[48:49], v[8:9], v[8:9]
	s_nop 0
	v_add_f32_e32 v59, v48, v49
	v_pk_mul_f32 v[48:49], v[10:11], v[10:11]
	s_nop 0
	v_add_f32_e32 v48, v59, v48
	v_add_f32_e32 v59, v48, v49
	s_waitcnt vmcnt(0)
	v_pk_mul_f32 v[48:49], v[0:1], v[0:1]
	s_nop 0
	v_add_f32_e32 v83, v48, v49
	v_pk_mul_f32 v[48:49], v[2:3], v[2:3]
	s_nop 0
	v_add_f32_e32 v48, v83, v48
	v_add_f32_e32 v48, v48, v49
	v_add_f32_e32 v49, v91, v90
	v_add_f32_e32 v49, v49, v92
	v_add_f32_e32 v49, v49, v50
	v_add_f32_e32 v50, v52, v51
	v_add_f32_e32 v51, v58, v57
	v_add_f32_e32 v50, v50, v53
	v_add_f32_e32 v51, v51, v59
	v_add_f32_e32 v50, v50, v56
	v_add_f32_e32 v48, v51, v48
	ds_bpermute_b32 v52, v74, v49
	ds_bpermute_b32 v53, v74, v50
	ds_bpermute_b32 v51, v74, v48
	v_cvt_pk_bf16_f32 v56, v60, v61
	v_cvt_pk_bf16_f32 v57, v62, v63
	s_waitcnt lgkmcnt(2)
	v_add_f32_e32 v49, v49, v52
	s_waitcnt lgkmcnt(1)
	v_add_f32_e32 v50, v50, v53
	s_waitcnt lgkmcnt(0)
	v_add_f32_e32 v48, v48, v51
	ds_bpermute_b32 v52, v75, v49
	ds_bpermute_b32 v53, v75, v50
	ds_bpermute_b32 v51, v75, v48
	global_store_dwordx2 v[84:85], v[86:87], off sc1
	global_store_dwordx2 v[84:85], v[88:89], off offset:512 sc1
	global_store_dwordx2 v[84:85], v[54:55], off offset:1024 sc1
	global_store_dwordx2 v[84:85], v[56:57], off offset:1536 sc1
	s_waitcnt lgkmcnt(2)
	v_add_f32_e32 v49, v49, v52
	s_waitcnt lgkmcnt(1)
	v_add_f32_e32 v50, v50, v53
	s_waitcnt lgkmcnt(0)
	v_add_f32_e32 v48, v48, v51
	ds_bpermute_b32 v52, v76, v49
	ds_bpermute_b32 v53, v76, v50
	ds_bpermute_b32 v51, v76, v48
	s_waitcnt lgkmcnt(2)
	v_add_f32_e32 v49, v49, v52
	s_waitcnt lgkmcnt(1)
	v_add_f32_e32 v50, v50, v53
	s_waitcnt lgkmcnt(0)
	v_add_f32_e32 v48, v48, v51
	ds_bpermute_b32 v52, v77, v49
	ds_bpermute_b32 v53, v77, v50
	ds_bpermute_b32 v51, v77, v48
	s_waitcnt lgkmcnt(2)
	v_add_f32_e32 v49, v49, v52
	s_waitcnt lgkmcnt(1)
	v_add_f32_e32 v50, v50, v53
	s_waitcnt lgkmcnt(0)
	v_add_f32_e32 v48, v48, v51
	ds_bpermute_b32 v52, v78, v49
	ds_bpermute_b32 v53, v78, v50
	ds_bpermute_b32 v51, v78, v48
	s_waitcnt lgkmcnt(2)
	v_add_f32_e32 v52, v49, v52
	s_waitcnt lgkmcnt(1)
	v_add_f32_e32 v50, v50, v53
	s_waitcnt lgkmcnt(0)
	v_add_f32_e32 v48, v48, v51
	ds_bpermute_b32 v53, v79, v52
	ds_bpermute_b32 v51, v79, v50
	ds_bpermute_b32 v49, v79, v48
	s_and_saveexec_b64 s[10:11], s[6:7]
	s_cbranch_execnz .LBB0_52
	s_or_b64 exec, exec, s[10:11]
	s_and_saveexec_b64 s[10:11], s[8:9]
	s_cbranch_execnz .LBB0_53

.LBB0_120:
	v_lshl_add_u32 v136, s58, 2, v147
	v_mul_f32_e32 v129, 0x3d372713, v124
	v_mul_f32_e32 v134, 0x3d372713, v125
	v_mul_f32_e32 v137, 0x3d372713, v126
	v_mul_f32_e32 v138, 0x3d372713, v127
	v_mul_f32_e32 v139, 0x3d372713, v116
	v_mul_f32_e32 v142, 0x3d372713, v117
	v_mul_f32_e32 v145, 0x3d372713, v118
	v_mul_f32_e32 v155, 0x3d372713, v119
	v_mul_f32_e32 v156, 0x3d372713, v108
	v_mul_f32_e32 v157, 0x3d372713, v109
	v_mul_f32_e32 v158, 0x3d372713, v110
	v_mul_f32_e32 v159, 0x3d372713, v111
	v_mul_f32_e32 v160, 0x3d372713, v100
	v_mul_f32_e32 v161, 0x3d372713, v101
	v_mul_f32_e32 v162, 0x3d372713, v102
	v_mul_f32_e32 v169, 0x3d372713, v103
	v_mul_f32_e32 v170, 0x3d372713, v92
	v_mul_f32_e32 v171, 0x3d372713, v93
	v_mul_f32_e32 v172, 0x3d372713, v94
	v_mul_f32_e32 v173, 0x3d372713, v95
	s_lshl_b32 s88, s86, 8
	v_cmp_lt_i32_e32 vcc, 63, v136
	v_mul_f32_e32 v135, v124, v129
	v_mul_f32_e32 v144, v125, v134
	v_mul_f32_e32 v141, v126, v137
	v_mul_f32_e32 v140, v127, v138
	v_mul_f32_e32 v143, v116, v139
	v_mul_f32_e32 v142, v117, v142
	v_mul_f32_e32 v139, v118, v145
	v_mul_f32_e32 v138, v119, v155
	v_mul_f32_e32 v168, v108, v156
	v_mul_f32_e32 v167, v109, v157
	v_mul_f32_e32 v166, v110, v158
	v_mul_f32_e32 v165, v111, v159
	v_mul_f32_e32 v164, v100, v160
	v_mul_f32_e32 v163, v101, v161
	v_mul_f32_e32 v162, v102, v162
	v_mul_f32_e32 v161, v103, v169
	v_mul_f32_e32 v160, v92, v170
	v_mul_f32_e32 v159, v93, v171
	v_mul_f32_e32 v158, v94, v172
	v_mul_f32_e32 v157, v95, v173
	v_mul_f32_e32 v156, 0x3d372713, v84
	v_mul_f32_e32 v155, 0x3d372713, v85
	v_mul_f32_e32 v137, 0x3d372713, v86
	v_mul_f32_e32 v129, 0x3d372713, v87
	s_and_saveexec_b64 s[58:59], vcc
	s_xor_b64 s[58:59], exec, s[58:59]
	s_cbranch_execz .LBB0_128
	v_fma_f32 v135, v124, v135, v124
	v_mul_f32_e32 v135, 0x3fcc422a, v135
	v_fma_f32 v144, v125, v144, v125
	v_mul_f32_e32 v135, 0xbfb8aa3b, v135
	v_mul_f32_e32 v144, 0x3fcc422a, v144
	v_fma_f32 v141, v126, v141, v126
	v_exp_f32_e32 v135, v135
	v_mul_f32_e32 v144, 0xbfb8aa3b, v144
	v_mul_f32_e32 v141, 0x3fcc422a, v141
	v_fma_f32 v140, v127, v140, v127
	v_exp_f32_e32 v145, v144
	v_mul_f32_e32 v141, 0xbfb8aa3b, v141
	v_mul_f32_e32 v140, 0x3fcc422a, v140
	v_exp_f32_e32 v141, v141
	v_mul_f32_e32 v140, 0xbfb8aa3b, v140
	v_exp_f32_e32 v169, v140
	v_add_f32_e32 v135, 1.0, v135
	v_rcp_f32_e32 v144, v135
	v_add_f32_e32 v135, 1.0, v145
	v_rcp_f32_e32 v145, v135
	v_add_f32_e32 v135, 1.0, v141
	v_rcp_f32_e32 v140, v135
	v_add_f32_e32 v135, 1.0, v169
	v_rcp_f32_e32 v141, v135
	v_fma_f32 v135, v116, v143, v116
	v_lshl_add_u32 v172, s95, 1, v146
	v_mul_f32_e32 v135, 0x3fcc422a, v135
	v_fma_f32 v142, v117, v142, v117
	v_subrev_u32_e32 v136, 64, v136
	v_ashrrev_i32_e32 v173, 31, v172
	v_mul_f32_e32 v135, 0xbfb8aa3b, v135
	v_mul_f32_e32 v142, 0x3fcc422a, v142
	v_fma_f32 v139, v118, v139, v118
	v_lshl_or_b32 v170, v136, 6, v148
	v_lshlrev_b64 v[172:173], 19, v[172:173]
	v_pk_mul_f32 v[144:145], v[124:125], v[144:145]
	v_pk_mul_f32 v[140:141], v[126:127], v[140:141]
	v_mov_b32_e32 v171, v128
	v_exp_f32_e32 v135, v135
	v_mul_f32_e32 v142, 0xbfb8aa3b, v142
	v_mul_f32_e32 v139, 0x3fcc422a, v139
	v_fma_f32 v138, v119, v138, v119
	v_lshl_add_u64 v[172:173], v[130:131], 0, v[172:173]
	v_cvt_pk_bf16_f32 v144, v144, v145
	v_cvt_pk_bf16_f32 v145, v140, v141
	v_lshlrev_b64 v[140:141], 8, v[170:171]
	v_exp_f32_e32 v143, v142
	v_mul_f32_e32 v139, 0xbfb8aa3b, v139
	v_mul_f32_e32 v138, 0x3fcc422a, v138
	v_lshl_add_u64 v[140:141], v[172:173], 0, v[140:141]
	v_exp_f32_e32 v139, v139
	v_mul_f32_e32 v138, 0xbfb8aa3b, v138
	global_store_dwordx2 v[140:141], v[144:145], off sc1
	ds_write_b16 v150, v144
	ds_write_b16_d16_hi v150, v144 offset:144
	v_exp_f32_e32 v144, v138
	v_add_f32_e32 v135, 1.0, v135
	v_rcp_f32_e32 v142, v135
	v_add_f32_e32 v135, 1.0, v143
	v_rcp_f32_e32 v143, v135
	v_add_f32_e32 v135, 1.0, v139
	v_rcp_f32_e32 v138, v135
	v_add_f32_e32 v135, 1.0, v144
	v_rcp_f32_e32 v139, v135
	ds_write_b16 v150, v145 offset:288
	ds_write_b16_d16_hi v150, v145 offset:432
	v_or_b32_e32 v144, 16, v170
	v_pk_mul_f32 v[142:143], v[116:117], v[142:143]
	v_pk_mul_f32 v[138:139], v[118:119], v[138:139]
	v_mov_b32_e32 v145, v128
	v_cvt_pk_bf16_f32 v142, v142, v143
	v_cvt_pk_bf16_f32 v143, v138, v139
	v_lshlrev_b64 v[138:139], 8, v[144:145]
	v_lshl_add_u64 v[138:139], v[172:173], 0, v[138:139]
	v_mul_f32_e32 v135, 0x3d372713, v120
	global_store_dwordx2 v[138:139], v[142:143], off sc1
	ds_write_b16 v150, v142 offset:32
	ds_write_b16_d16_hi v150, v142 offset:176
	v_mul_f32_e32 v135, v120, v135
	v_mul_f32_e32 v142, 0x3d372713, v121
	v_fma_f32 v135, v120, v135, v120
	v_mul_f32_e32 v142, v121, v142
	v_mul_f32_e32 v135, 0x3fcc422a, v135
	v_fma_f32 v142, v121, v142, v121
	v_mul_f32_e32 v135, 0xbfb8aa3b, v135
	v_mul_f32_e32 v142, 0x3fcc422a, v142
	v_exp_f32_e32 v135, v135
	v_mul_f32_e32 v142, 0xbfb8aa3b, v142
	v_exp_f32_e32 v142, v142
	v_mul_f32_e32 v145, 0x3d372713, v123
	v_add_f32_e32 v135, 1.0, v135
	v_rcp_f32_e32 v144, v135
	v_add_f32_e32 v135, 1.0, v142
	v_mul_f32_e32 v142, 0x3d372713, v122
	v_mul_f32_e32 v142, v122, v142
	v_fma_f32 v142, v122, v142, v122
	v_mul_f32_e32 v145, v123, v145
	v_mul_f32_e32 v142, 0x3fcc422a, v142
	v_fma_f32 v145, v123, v145, v123
	v_mul_f32_e32 v142, 0xbfb8aa3b, v142
	v_mul_f32_e32 v145, 0x3fcc422a, v145
	v_exp_f32_e32 v142, v142
	v_mul_f32_e32 v145, 0xbfb8aa3b, v145
	v_exp_f32_e32 v169, v145
	v_rcp_f32_e32 v145, v135
	v_add_f32_e32 v135, 1.0, v142
	v_rcp_f32_e32 v174, v135
	v_add_f32_e32 v135, 1.0, v169
	v_rcp_f32_e32 v175, v135
	ds_write_b16 v150, v143 offset:320
	ds_write_b16_d16_hi v150, v143 offset:464
	v_or_b32_e32 v142, 32, v170
	v_mov_b32_e32 v143, v128
	v_pk_mul_f32 v[144:145], v[120:121], v[144:145]
	v_pk_mul_f32 v[174:175], v[122:123], v[174:175]
	v_lshlrev_b64 v[142:143], 8, v[142:143]
	v_cvt_pk_bf16_f32 v144, v144, v145
	v_cvt_pk_bf16_f32 v145, v174, v175
	v_lshl_add_u64 v[142:143], v[172:173], 0, v[142:143]
	v_mul_f32_e32 v135, 0x3d372713, v112
	global_store_dwordx2 v[142:143], v[144:145], off sc1
	ds_write_b16 v150, v144 offset:64
	ds_write_b16_d16_hi v150, v144 offset:208
	v_mul_f32_e32 v135, v112, v135
	v_mul_f32_e32 v144, 0x3d372713, v113
	v_fma_f32 v135, v112, v135, v112
	v_mul_f32_e32 v144, v113, v144
	v_mul_f32_e32 v135, 0x3fcc422a, v135
	v_fma_f32 v144, v113, v144, v113
	v_mul_f32_e32 v135, 0xbfb8aa3b, v135
	v_mul_f32_e32 v144, 0x3fcc422a, v144
	v_exp_f32_e32 v135, v135
	v_mul_f32_e32 v144, 0xbfb8aa3b, v144
	v_exp_f32_e32 v144, v144
	v_mul_f32_e32 v169, 0x3d372713, v115
	v_add_f32_e32 v135, 1.0, v135
	v_rcp_f32_e32 v174, v135
	v_add_f32_e32 v135, 1.0, v144
	v_mul_f32_e32 v144, 0x3d372713, v114
	v_mul_f32_e32 v144, v114, v144
	v_fma_f32 v144, v114, v144, v114
	v_mul_f32_e32 v169, v115, v169
	v_mul_f32_e32 v144, 0x3fcc422a, v144
	v_fma_f32 v169, v115, v169, v115
	v_mul_f32_e32 v144, 0xbfb8aa3b, v144
	v_mul_f32_e32 v169, 0x3fcc422a, v169
	v_exp_f32_e32 v144, v144
	v_mul_f32_e32 v169, 0xbfb8aa3b, v169
	v_exp_f32_e32 v169, v169
	v_rcp_f32_e32 v175, v135
	v_add_f32_e32 v135, 1.0, v144
	v_rcp_f32_e32 v176, v135
	v_add_f32_e32 v135, 1.0, v169
	v_rcp_f32_e32 v177, v135
	v_fma_f32 v135, v108, v168, v108
	v_mul_f32_e32 v135, 0x3fcc422a, v135
	v_fma_f32 v167, v109, v167, v109
	v_mul_f32_e32 v135, 0xbfb8aa3b, v135
	v_mul_f32_e32 v167, 0x3fcc422a, v167
	v_fma_f32 v166, v110, v166, v110
	v_exp_f32_e32 v135, v135
	v_mul_f32_e32 v167, 0xbfb8aa3b, v167
	v_mul_f32_e32 v166, 0x3fcc422a, v166
	v_fma_f32 v165, v111, v165, v111
	v_exp_f32_e32 v167, v167
	v_mul_f32_e32 v166, 0xbfb8aa3b, v166
	v_mul_f32_e32 v165, 0x3fcc422a, v165
	v_exp_f32_e32 v166, v166
	v_mul_f32_e32 v165, 0xbfb8aa3b, v165
	v_exp_f32_e32 v165, v165
	v_add_f32_e32 v135, 1.0, v135
	v_rcp_f32_e32 v168, v135
	v_add_f32_e32 v135, 1.0, v167
	v_rcp_f32_e32 v169, v135
	v_add_f32_e32 v135, 1.0, v166
	v_rcp_f32_e32 v166, v135
	v_add_f32_e32 v135, 1.0, v165
	v_rcp_f32_e32 v167, v135
	v_fma_f32 v135, v100, v164, v100
	v_mul_f32_e32 v135, 0x3fcc422a, v135
	v_fma_f32 v163, v101, v163, v101
	v_mul_f32_e32 v135, 0xbfb8aa3b, v135
	v_mul_f32_e32 v163, 0x3fcc422a, v163
	v_fma_f32 v162, v102, v162, v102
	v_exp_f32_e32 v135, v135
	v_mul_f32_e32 v163, 0xbfb8aa3b, v163
	v_mul_f32_e32 v162, 0x3fcc422a, v162
	v_fma_f32 v161, v103, v161, v103
	v_exp_f32_e32 v163, v163
	v_mul_f32_e32 v162, 0xbfb8aa3b, v162
	v_mul_f32_e32 v161, 0x3fcc422a, v161
	v_exp_f32_e32 v162, v162
	v_mul_f32_e32 v161, 0xbfb8aa3b, v161
	v_exp_f32_e32 v161, v161
	v_add_f32_e32 v135, 1.0, v135
	v_rcp_f32_e32 v164, v135
	v_add_f32_e32 v135, 1.0, v163
	v_rcp_f32_e32 v165, v135
	v_add_f32_e32 v135, 1.0, v162
	v_rcp_f32_e32 v162, v135
	v_add_f32_e32 v135, 1.0, v161
	v_rcp_f32_e32 v163, v135
	v_mul_f32_e32 v135, 0x3d372713, v104
	v_mul_f32_e32 v135, v104, v135
	v_mul_f32_e32 v161, 0x3d372713, v105
	v_fma_f32 v135, v104, v135, v104
	v_mul_f32_e32 v161, v105, v161
	v_mul_f32_e32 v135, 0x3fcc422a, v135
	v_fma_f32 v161, v105, v161, v105
	v_mul_f32_e32 v135, 0xbfb8aa3b, v135
	v_mul_f32_e32 v161, 0x3fcc422a, v161
	v_exp_f32_e32 v135, v135
	v_mul_f32_e32 v161, 0xbfb8aa3b, v161
	v_exp_f32_e32 v161, v161
	v_pk_mul_f32 v[164:165], v[100:101], v[164:165]
	v_pk_mul_f32 v[162:163], v[102:103], v[162:163]
	v_add_f32_e32 v135, 1.0, v135
	v_cvt_pk_bf16_f32 v164, v164, v165
	v_cvt_pk_bf16_f32 v165, v162, v163
	v_rcp_f32_e32 v162, v135
	v_add_f32_e32 v135, 1.0, v161
	v_mul_f32_e32 v161, 0x3d372713, v106
	v_mul_f32_e32 v161, v106, v161
	v_mul_f32_e32 v163, 0x3d372713, v107
	v_fma_f32 v161, v106, v161, v106
	v_mul_f32_e32 v163, v107, v163
	ds_write_b16 v150, v145 offset:352
	ds_write_b16_d16_hi v150, v145 offset:496
	v_or_b32_e32 v144, 48, v170
	v_mov_b32_e32 v145, v128
	v_mul_f32_e32 v161, 0x3fcc422a, v161
	v_fma_f32 v163, v107, v163, v107
	v_pk_mul_f32 v[170:171], v[112:113], v[174:175]
	v_pk_mul_f32 v[174:175], v[114:115], v[176:177]
	v_lshlrev_b64 v[144:145], 8, v[144:145]
	v_pk_mul_f32 v[168:169], v[108:109], v[168:169]
	v_pk_mul_f32 v[166:167], v[110:111], v[166:167]
	v_mul_f32_e32 v161, 0xbfb8aa3b, v161
	v_mul_f32_e32 v163, 0x3fcc422a, v163
	v_cvt_pk_bf16_f32 v170, v170, v171
	v_cvt_pk_bf16_f32 v171, v174, v175
	v_lshl_add_u64 v[144:145], v[172:173], 0, v[144:145]
	v_cvt_pk_bf16_f32 v168, v168, v169
	v_cvt_pk_bf16_f32 v169, v166, v167
	v_exp_f32_e32 v161, v161
	v_mul_f32_e32 v163, 0xbfb8aa3b, v163
	global_store_dwordx2 v[144:145], v[170:171], off sc1
	ds_write_b16 v150, v170 offset:96
	ds_write_b16_d16_hi v150, v170 offset:240
	ds_write_b16 v150, v171 offset:384
	ds_write_b16_d16_hi v150, v171 offset:528
	global_store_dwordx2 v[140:141], v[168:169], off offset:32 sc1
	ds_write_b16 v150, v168 offset:2304
	ds_write_b16_d16_hi v150, v168 offset:2448
	ds_write_b16 v150, v169 offset:2592
	ds_write_b16_d16_hi v150, v169 offset:2736
	global_store_dwordx2 v[138:139], v[164:165], off offset:32 sc1
	ds_write_b16 v150, v164 offset:2336
	ds_write_b16_d16_hi v150, v164 offset:2480
	v_exp_f32_e32 v164, v163
	v_rcp_f32_e32 v163, v135
	v_add_f32_e32 v135, 1.0, v161
	v_rcp_f32_e32 v166, v135
	v_add_f32_e32 v135, 1.0, v164
	v_rcp_f32_e32 v167, v135
	v_mul_f32_e32 v135, 0x3d372713, v96
	v_mul_f32_e32 v135, v96, v135
	v_mul_f32_e32 v161, 0x3d372713, v97
	v_fma_f32 v135, v96, v135, v96
	v_mul_f32_e32 v161, v97, v161
	v_mul_f32_e32 v135, 0x3fcc422a, v135
	v_fma_f32 v161, v97, v161, v97
	v_mul_f32_e32 v135, 0xbfb8aa3b, v135
	v_mul_f32_e32 v161, 0x3fcc422a, v161
	v_exp_f32_e32 v135, v135
	v_mul_f32_e32 v161, 0xbfb8aa3b, v161
	v_exp_f32_e32 v161, v161
	ds_write_b16 v150, v165 offset:2624
	ds_write_b16_d16_hi v150, v165 offset:2768
	v_pk_mul_f32 v[162:163], v[104:105], v[162:163]
	v_pk_mul_f32 v[164:165], v[106:107], v[166:167]
	v_add_f32_e32 v135, 1.0, v135
	v_cvt_pk_bf16_f32 v162, v162, v163
	v_cvt_pk_bf16_f32 v163, v164, v165
	v_rcp_f32_e32 v164, v135
	v_add_f32_e32 v135, 1.0, v161
	v_mul_f32_e32 v161, 0x3d372713, v98
	global_store_dwordx2 v[142:143], v[162:163], off offset:32 sc1
	ds_write_b16 v150, v162 offset:2368
	ds_write_b16_d16_hi v150, v162 offset:2512
	v_mul_f32_e32 v161, v98, v161
	v_mul_f32_e32 v162, 0x3d372713, v99
	v_fma_f32 v161, v98, v161, v98
	v_mul_f32_e32 v162, v99, v162
	v_mul_f32_e32 v161, 0x3fcc422a, v161
	v_fma_f32 v162, v99, v162, v99
	v_mul_f32_e32 v161, 0xbfb8aa3b, v161
	v_mul_f32_e32 v162, 0x3fcc422a, v162
	v_exp_f32_e32 v161, v161
	v_mul_f32_e32 v162, 0xbfb8aa3b, v162
	v_exp_f32_e32 v162, v162
	v_rcp_f32_e32 v165, v135
	v_add_f32_e32 v135, 1.0, v161
	v_rcp_f32_e32 v166, v135
	v_add_f32_e32 v135, 1.0, v162
	v_rcp_f32_e32 v167, v135
	v_fma_f32 v135, v92, v160, v92
	v_mul_f32_e32 v135, 0x3fcc422a, v135
	v_fma_f32 v159, v93, v159, v93
	v_mul_f32_e32 v135, 0xbfb8aa3b, v135
	v_mul_f32_e32 v159, 0x3fcc422a, v159
	v_fma_f32 v158, v94, v158, v94
	v_exp_f32_e32 v135, v135
	v_mul_f32_e32 v159, 0xbfb8aa3b, v159
	v_mul_f32_e32 v158, 0x3fcc422a, v158
	v_fma_f32 v157, v95, v157, v95
	v_exp_f32_e32 v159, v159
	v_mul_f32_e32 v158, 0xbfb8aa3b, v158
	v_mul_f32_e32 v157, 0x3fcc422a, v157
	v_exp_f32_e32 v158, v158
	v_mul_f32_e32 v157, 0xbfb8aa3b, v157
	v_exp_f32_e32 v157, v157
	v_add_f32_e32 v135, 1.0, v135
	v_rcp_f32_e32 v160, v135
	v_add_f32_e32 v135, 1.0, v159
	v_rcp_f32_e32 v161, v135
	v_add_f32_e32 v135, 1.0, v158
	v_rcp_f32_e32 v158, v135
	v_add_f32_e32 v135, 1.0, v157
	v_rcp_f32_e32 v159, v135
	v_mul_f32_e32 v135, v84, v156
	v_fma_f32 v135, v84, v135, v84
	v_mul_f32_e32 v155, v85, v155
	v_mul_f32_e32 v129, v87, v129
	v_mul_f32_e32 v135, 0x3fcc422a, v135
	v_fma_f32 v155, v85, v155, v85
	v_mul_f32_e32 v137, v86, v137
	v_fma_f32 v129, v87, v129, v87
	v_mul_f32_e32 v135, 0xbfb8aa3b, v135
	v_mul_f32_e32 v155, 0x3fcc422a, v155
	v_fma_f32 v137, v86, v137, v86
	v_mul_f32_e32 v129, 0x3fcc422a, v129
	v_exp_f32_e32 v135, v135
	v_mul_f32_e32 v155, 0xbfb8aa3b, v155
	v_mul_f32_e32 v137, 0x3fcc422a, v137
	v_mul_f32_e32 v129, 0xbfb8aa3b, v129
	v_exp_f32_e32 v155, v155
	v_mul_f32_e32 v137, 0xbfb8aa3b, v137
	v_exp_f32_e32 v129, v129
	v_exp_f32_e32 v137, v137
	v_add_f32_e32 v135, 1.0, v135
	v_pk_mul_f32 v[160:161], v[92:93], v[160:161]
	v_pk_mul_f32 v[158:159], v[94:95], v[158:159]
	v_rcp_f32_e32 v156, v135
	v_add_f32_e32 v135, 1.0, v155
	v_add_f32_e32 v129, 1.0, v129
	v_cvt_pk_bf16_f32 v160, v160, v161
	v_cvt_pk_bf16_f32 v161, v158, v159
	v_rcp_f32_e32 v157, v135
	v_add_f32_e32 v135, 1.0, v137
	v_rcp_f32_e32 v159, v129
	v_mul_f32_e32 v129, 0x3d372713, v88
	v_rcp_f32_e32 v158, v135
	v_mul_f32_e32 v129, v88, v129
	v_mul_f32_e32 v135, 0x3d372713, v89
	v_fma_f32 v129, v88, v129, v88
	v_mul_f32_e32 v135, v89, v135
	v_mul_f32_e32 v129, 0x3fcc422a, v129
	v_fma_f32 v135, v89, v135, v89
	v_mul_f32_e32 v129, 0xbfb8aa3b, v129
	v_mul_f32_e32 v135, 0x3fcc422a, v135
	v_exp_f32_e32 v129, v129
	v_mul_f32_e32 v135, 0xbfb8aa3b, v135
	v_exp_f32_e32 v135, v135
	v_pk_mul_f32 v[156:157], v[84:85], v[156:157]
	v_pk_mul_f32 v[158:159], v[86:87], v[158:159]
	v_add_f32_e32 v129, 1.0, v129
	v_cvt_pk_bf16_f32 v156, v156, v157
	v_cvt_pk_bf16_f32 v157, v158, v159
	v_rcp_f32_e32 v158, v129
	v_add_f32_e32 v129, 1.0, v135
	v_mul_f32_e32 v135, 0x3d372713, v90
	v_mul_f32_e32 v135, v90, v135
	v_mul_f32_e32 v137, 0x3d372713, v91
	v_fma_f32 v135, v90, v135, v90
	v_mul_f32_e32 v137, v91, v137
	v_mul_f32_e32 v135, 0x3fcc422a, v135
	v_fma_f32 v137, v91, v137, v91
	v_mul_f32_e32 v135, 0xbfb8aa3b, v135
	v_mul_f32_e32 v137, 0x3fcc422a, v137
	v_exp_f32_e32 v135, v135
	v_mul_f32_e32 v137, 0xbfb8aa3b, v137
	v_exp_f32_e32 v137, v137
	ds_write_b16 v150, v163 offset:2656
	ds_write_b16_d16_hi v150, v163 offset:2800
	v_pk_mul_f32 v[162:163], v[96:97], v[164:165]
	v_pk_mul_f32 v[164:165], v[98:99], v[166:167]
	v_cvt_pk_bf16_f32 v162, v162, v163
	v_cvt_pk_bf16_f32 v163, v164, v165
	v_rcp_f32_e32 v159, v129
	v_add_f32_e32 v129, 1.0, v135
	global_store_dwordx2 v[144:145], v[162:163], off offset:32 sc1
	ds_write_b16 v150, v162 offset:2400
	ds_write_b16_d16_hi v150, v162 offset:2544
	ds_write_b16 v150, v163 offset:2688
	ds_write_b16_d16_hi v150, v163 offset:2832
	global_store_dwordx2 v[140:141], v[160:161], off offset:64 sc1
	ds_write_b16 v150, v160 offset:4608
	ds_write_b16_d16_hi v150, v160 offset:4752
	v_rcp_f32_e32 v160, v129
	v_add_f32_e32 v129, 1.0, v137
	ds_write_b16 v150, v161 offset:4896
	ds_write_b16_d16_hi v150, v161 offset:5040
	v_rcp_f32_e32 v161, v129
	v_mul_f32_e32 v129, 0x3d372713, v80
	v_mul_f32_e32 v129, v80, v129
	v_mul_f32_e32 v135, 0x3d372713, v81
	v_fma_f32 v129, v80, v129, v80
	v_mul_f32_e32 v135, v81, v135
	v_mul_f32_e32 v129, 0x3fcc422a, v129
	v_fma_f32 v135, v81, v135, v81
	v_mul_f32_e32 v129, 0xbfb8aa3b, v129
	v_mul_f32_e32 v135, 0x3fcc422a, v135
	v_exp_f32_e32 v129, v129
	v_mul_f32_e32 v135, 0xbfb8aa3b, v135
	v_exp_f32_e32 v135, v135
	global_store_dwordx2 v[138:139], v[156:157], off offset:64 sc1
	ds_write_b16 v150, v156 offset:4640
	ds_write_b16_d16_hi v150, v156 offset:4784
	ds_write_b16 v150, v157 offset:4928
	ds_write_b16_d16_hi v150, v157 offset:5072
	v_pk_mul_f32 v[156:157], v[88:89], v[158:159]
	v_pk_mul_f32 v[158:159], v[90:91], v[160:161]
	v_add_f32_e32 v129, 1.0, v129
	v_cvt_pk_bf16_f32 v156, v156, v157
	v_cvt_pk_bf16_f32 v157, v158, v159
	v_rcp_f32_e32 v158, v129
	v_add_f32_e32 v129, 1.0, v135
	v_mul_f32_e32 v135, 0x3d372713, v82
	v_mul_f32_e32 v135, v82, v135
	v_mul_f32_e32 v137, 0x3d372713, v83
	v_fma_f32 v135, v82, v135, v82
	v_mul_f32_e32 v137, v83, v137
	v_mul_f32_e32 v135, 0x3fcc422a, v135
	v_fma_f32 v137, v83, v137, v83
	v_mul_f32_e32 v135, 0xbfb8aa3b, v135
	v_mul_f32_e32 v137, 0x3fcc422a, v137
	v_exp_f32_e32 v135, v135
	v_mul_f32_e32 v137, 0xbfb8aa3b, v137
	v_exp_f32_e32 v137, v137
	v_rcp_f32_e32 v159, v129
	v_add_f32_e32 v129, 1.0, v135
	v_rcp_f32_e32 v160, v129
	v_add_f32_e32 v129, 1.0, v137
	v_rcp_f32_e32 v161, v129
	v_mul_f32_e32 v129, 0x3d372713, v76
	v_mul_f32_e32 v129, v76, v129
	v_mul_f32_e32 v135, 0x3d372713, v77
	v_fma_f32 v129, v76, v129, v76
	v_mul_f32_e32 v135, v77, v135
	v_mul_f32_e32 v129, 0x3fcc422a, v129
	v_fma_f32 v135, v77, v135, v77
	v_mul_f32_e32 v129, 0xbfb8aa3b, v129
	v_mul_f32_e32 v135, 0x3fcc422a, v135
	v_exp_f32_e32 v129, v129
	v_mul_f32_e32 v135, 0xbfb8aa3b, v135
	v_exp_f32_e32 v135, v135
	global_store_dwordx2 v[142:143], v[156:157], off offset:64 sc1
	ds_write_b16 v150, v156 offset:4672
	ds_write_b16_d16_hi v150, v156 offset:4816
	ds_write_b16 v150, v157 offset:4960
	ds_write_b16_d16_hi v150, v157 offset:5104
	v_pk_mul_f32 v[156:157], v[80:81], v[158:159]
	v_pk_mul_f32 v[158:159], v[82:83], v[160:161]
	v_add_f32_e32 v129, 1.0, v129
	v_cvt_pk_bf16_f32 v156, v156, v157
	v_cvt_pk_bf16_f32 v157, v158, v159
	v_rcp_f32_e32 v158, v129
	v_add_f32_e32 v129, 1.0, v135
	v_mul_f32_e32 v135, 0x3d372713, v78
	v_mul_f32_e32 v135, v78, v135
	v_mul_f32_e32 v137, 0x3d372713, v79
	v_fma_f32 v135, v78, v135, v78
	v_mul_f32_e32 v137, v79, v137
	v_mul_f32_e32 v135, 0x3fcc422a, v135
	v_fma_f32 v137, v79, v137, v79
	v_mul_f32_e32 v135, 0xbfb8aa3b, v135
	v_mul_f32_e32 v137, 0x3fcc422a, v137
	v_exp_f32_e32 v135, v135
	v_mul_f32_e32 v137, 0xbfb8aa3b, v137
	v_exp_f32_e32 v137, v137
	v_rcp_f32_e32 v159, v129
	v_add_f32_e32 v129, 1.0, v135
	v_rcp_f32_e32 v160, v129
	v_add_f32_e32 v129, 1.0, v137
	v_rcp_f32_e32 v161, v129
	v_mul_f32_e32 v129, 0x3d372713, v68
	v_mul_f32_e32 v129, v68, v129
	v_mul_f32_e32 v135, 0x3d372713, v69
	v_fma_f32 v129, v68, v129, v68
	v_mul_f32_e32 v135, v69, v135
	v_mul_f32_e32 v129, 0x3fcc422a, v129
	v_fma_f32 v135, v69, v135, v69
	v_mul_f32_e32 v129, 0xbfb8aa3b, v129
	v_mul_f32_e32 v135, 0x3fcc422a, v135
	v_exp_f32_e32 v129, v129
	v_mul_f32_e32 v135, 0xbfb8aa3b, v135
	v_exp_f32_e32 v135, v135
	global_store_dwordx2 v[144:145], v[156:157], off offset:64 sc1
	ds_write_b16 v150, v156 offset:4704
	ds_write_b16_d16_hi v150, v156 offset:4848
	ds_write_b16 v150, v157 offset:4992
	ds_write_b16_d16_hi v150, v157 offset:5136
	v_pk_mul_f32 v[156:157], v[76:77], v[158:159]
	v_pk_mul_f32 v[158:159], v[78:79], v[160:161]
	v_add_f32_e32 v129, 1.0, v129
	v_cvt_pk_bf16_f32 v156, v156, v157
	v_cvt_pk_bf16_f32 v157, v158, v159
	v_rcp_f32_e32 v158, v129
	v_add_f32_e32 v129, 1.0, v135
	v_mul_f32_e32 v135, 0x3d372713, v70
	v_mul_f32_e32 v135, v70, v135
	v_mul_f32_e32 v137, 0x3d372713, v71
	v_fma_f32 v135, v70, v135, v70
	v_mul_f32_e32 v137, v71, v137
	v_mul_f32_e32 v135, 0x3fcc422a, v135
	v_fma_f32 v137, v71, v137, v71
	v_mul_f32_e32 v135, 0xbfb8aa3b, v135
	v_mul_f32_e32 v137, 0x3fcc422a, v137
	v_exp_f32_e32 v135, v135
	v_mul_f32_e32 v137, 0xbfb8aa3b, v137
	v_exp_f32_e32 v137, v137
	v_rcp_f32_e32 v159, v129
	v_add_f32_e32 v129, 1.0, v135
	v_rcp_f32_e32 v160, v129
	v_add_f32_e32 v129, 1.0, v137
	v_rcp_f32_e32 v161, v129
	v_mul_f32_e32 v129, 0x3d372713, v72
	v_mul_f32_e32 v129, v72, v129
	v_mul_f32_e32 v135, 0x3d372713, v73
	v_fma_f32 v129, v72, v129, v72
	v_mul_f32_e32 v135, v73, v135
	v_mul_f32_e32 v129, 0x3fcc422a, v129
	v_fma_f32 v135, v73, v135, v73
	v_mul_f32_e32 v129, 0xbfb8aa3b, v129
	v_mul_f32_e32 v135, 0x3fcc422a, v135
	v_exp_f32_e32 v129, v129
	v_mul_f32_e32 v135, 0xbfb8aa3b, v135
	v_exp_f32_e32 v135, v135
	global_store_dwordx2 v[140:141], v[156:157], off offset:96 sc1
	ds_write_b16 v150, v156 offset:6912
	ds_write_b16_d16_hi v150, v156 offset:7056
	ds_write_b16 v150, v157 offset:7200
	ds_write_b16_d16_hi v150, v157 offset:7344
	v_pk_mul_f32 v[156:157], v[68:69], v[158:159]
	v_pk_mul_f32 v[158:159], v[70:71], v[160:161]
	v_add_f32_e32 v129, 1.0, v129
	v_cvt_pk_bf16_f32 v156, v156, v157
	v_cvt_pk_bf16_f32 v157, v158, v159
	v_rcp_f32_e32 v158, v129
	v_add_f32_e32 v129, 1.0, v135
	v_mul_f32_e32 v135, 0x3d372713, v74
	v_mul_f32_e32 v135, v74, v135
	v_mul_f32_e32 v137, 0x3d372713, v75
	v_fma_f32 v135, v74, v135, v74
	v_mul_f32_e32 v137, v75, v137
	v_mul_f32_e32 v135, 0x3fcc422a, v135
	v_fma_f32 v137, v75, v137, v75
	v_mul_f32_e32 v135, 0xbfb8aa3b, v135
	v_mul_f32_e32 v137, 0x3fcc422a, v137
	v_exp_f32_e32 v135, v135
	v_mul_f32_e32 v137, 0xbfb8aa3b, v137
	v_exp_f32_e32 v137, v137
	v_rcp_f32_e32 v159, v129
	v_add_f32_e32 v129, 1.0, v135
	v_rcp_f32_e32 v160, v129
	v_add_f32_e32 v129, 1.0, v137
	v_rcp_f32_e32 v161, v129
	v_mul_f32_e32 v129, 0x3d372713, v64
	v_mul_f32_e32 v129, v64, v129
	v_mul_f32_e32 v135, 0x3d372713, v65
	v_fma_f32 v129, v64, v129, v64
	v_mul_f32_e32 v135, v65, v135
	v_mul_f32_e32 v129, 0x3fcc422a, v129
	v_fma_f32 v135, v65, v135, v65
	v_mul_f32_e32 v129, 0xbfb8aa3b, v129
	v_mul_f32_e32 v135, 0x3fcc422a, v135
	v_exp_f32_e32 v129, v129
	v_mul_f32_e32 v135, 0xbfb8aa3b, v135
	v_exp_f32_e32 v135, v135
	global_store_dwordx2 v[138:139], v[156:157], off offset:96 sc1
	ds_write_b16 v150, v156 offset:6944
	ds_write_b16_d16_hi v150, v156 offset:7088
	ds_write_b16 v150, v157 offset:7232
	ds_write_b16_d16_hi v150, v157 offset:7376
	v_pk_mul_f32 v[156:157], v[72:73], v[158:159]
	v_pk_mul_f32 v[158:159], v[74:75], v[160:161]
	v_add_f32_e32 v129, 1.0, v129
	v_cvt_pk_bf16_f32 v156, v156, v157
	v_cvt_pk_bf16_f32 v157, v158, v159
	v_rcp_f32_e32 v158, v129
	v_add_f32_e32 v129, 1.0, v135
	v_mul_f32_e32 v135, 0x3d372713, v66
	v_mul_f32_e32 v135, v66, v135
	v_mul_f32_e32 v137, 0x3d372713, v67
	v_fma_f32 v135, v66, v135, v66
	v_mul_f32_e32 v137, v67, v137
	v_mul_f32_e32 v135, 0x3fcc422a, v135
	v_fma_f32 v137, v67, v137, v67
	v_mul_f32_e32 v135, 0xbfb8aa3b, v135
	v_mul_f32_e32 v137, 0x3fcc422a, v137
	v_exp_f32_e32 v135, v135
	v_mul_f32_e32 v137, 0xbfb8aa3b, v137
	v_exp_f32_e32 v137, v137
	v_rcp_f32_e32 v159, v129
	v_add_f32_e32 v129, 1.0, v135
	v_rcp_f32_e32 v160, v129
	v_add_f32_e32 v129, 1.0, v137
	v_rcp_f32_e32 v161, v129
	v_mul_f32_e32 v129, 0x3d372713, v60
	v_mul_f32_e32 v129, v60, v129
	v_mul_f32_e32 v135, 0x3d372713, v61
	v_fma_f32 v129, v60, v129, v60
	v_mul_f32_e32 v135, v61, v135
	v_mul_f32_e32 v129, 0x3fcc422a, v129
	v_fma_f32 v135, v61, v135, v61
	v_mul_f32_e32 v129, 0xbfb8aa3b, v129
	v_mul_f32_e32 v135, 0x3fcc422a, v135
	v_exp_f32_e32 v129, v129
	v_mul_f32_e32 v135, 0xbfb8aa3b, v135
	v_exp_f32_e32 v135, v135
	global_store_dwordx2 v[142:143], v[156:157], off offset:96 sc1
	ds_write_b16 v150, v156 offset:6976
	ds_write_b16_d16_hi v150, v156 offset:7120
	ds_write_b16 v150, v157 offset:7264
	ds_write_b16_d16_hi v150, v157 offset:7408
	v_pk_mul_f32 v[156:157], v[64:65], v[158:159]
	v_pk_mul_f32 v[158:159], v[66:67], v[160:161]
	v_add_f32_e32 v129, 1.0, v129
	v_cvt_pk_bf16_f32 v156, v156, v157
	v_cvt_pk_bf16_f32 v157, v158, v159
	v_rcp_f32_e32 v158, v129
	v_add_f32_e32 v129, 1.0, v135
	v_mul_f32_e32 v135, 0x3d372713, v62
	v_mul_f32_e32 v135, v62, v135
	v_mul_f32_e32 v137, 0x3d372713, v63
	v_fma_f32 v135, v62, v135, v62
	v_mul_f32_e32 v137, v63, v137
	v_mul_f32_e32 v135, 0x3fcc422a, v135
	v_fma_f32 v137, v63, v137, v63
	v_mul_f32_e32 v135, 0xbfb8aa3b, v135
	v_mul_f32_e32 v137, 0x3fcc422a, v137
	v_exp_f32_e32 v135, v135
	v_mul_f32_e32 v137, 0xbfb8aa3b, v137
	v_exp_f32_e32 v137, v137
	v_rcp_f32_e32 v159, v129
	v_add_f32_e32 v129, 1.0, v135
	v_rcp_f32_e32 v160, v129
	v_add_f32_e32 v129, 1.0, v137
	v_rcp_f32_e32 v161, v129
	v_mul_f32_e32 v129, 0x3d372713, v52
	v_mul_f32_e32 v129, v52, v129
	v_mul_f32_e32 v135, 0x3d372713, v53
	v_fma_f32 v129, v52, v129, v52
	v_mul_f32_e32 v135, v53, v135
	v_mul_f32_e32 v129, 0x3fcc422a, v129
	v_fma_f32 v135, v53, v135, v53
	v_mul_f32_e32 v129, 0xbfb8aa3b, v129
	v_mul_f32_e32 v135, 0x3fcc422a, v135
	v_exp_f32_e32 v129, v129
	v_mul_f32_e32 v135, 0xbfb8aa3b, v135
	v_exp_f32_e32 v135, v135
	global_store_dwordx2 v[144:145], v[156:157], off offset:96 sc1
	ds_write_b16 v150, v156 offset:7008
	ds_write_b16_d16_hi v150, v156 offset:7152
	ds_write_b16 v150, v157 offset:7296
	ds_write_b16_d16_hi v150, v157 offset:7440
	v_pk_mul_f32 v[156:157], v[60:61], v[158:159]
	v_pk_mul_f32 v[158:159], v[62:63], v[160:161]
	v_add_f32_e32 v129, 1.0, v129
	v_cvt_pk_bf16_f32 v156, v156, v157
	v_cvt_pk_bf16_f32 v157, v158, v159
	v_rcp_f32_e32 v158, v129
	v_add_f32_e32 v129, 1.0, v135
	v_mul_f32_e32 v135, 0x3d372713, v54
	v_mul_f32_e32 v135, v54, v135
	v_mul_f32_e32 v137, 0x3d372713, v55
	v_fma_f32 v135, v54, v135, v54
	v_mul_f32_e32 v137, v55, v137
	v_mul_f32_e32 v135, 0x3fcc422a, v135
	v_fma_f32 v137, v55, v137, v55
	v_mul_f32_e32 v135, 0xbfb8aa3b, v135
	v_mul_f32_e32 v137, 0x3fcc422a, v137
	v_exp_f32_e32 v135, v135
	v_mul_f32_e32 v137, 0xbfb8aa3b, v137
	v_exp_f32_e32 v137, v137
	v_rcp_f32_e32 v159, v129
	v_add_f32_e32 v129, 1.0, v135
	v_rcp_f32_e32 v160, v129
	v_add_f32_e32 v129, 1.0, v137
	v_rcp_f32_e32 v161, v129
	v_mul_f32_e32 v129, 0x3d372713, v56
	v_mul_f32_e32 v129, v56, v129
	v_mul_f32_e32 v135, 0x3d372713, v57
	v_fma_f32 v129, v56, v129, v56
	v_mul_f32_e32 v135, v57, v135
	v_mul_f32_e32 v129, 0x3fcc422a, v129
	v_fma_f32 v135, v57, v135, v57
	v_mul_f32_e32 v129, 0xbfb8aa3b, v129
	v_mul_f32_e32 v135, 0x3fcc422a, v135
	v_exp_f32_e32 v129, v129
	v_mul_f32_e32 v135, 0xbfb8aa3b, v135
	v_exp_f32_e32 v135, v135
	global_store_dwordx2 v[140:141], v[156:157], off offset:128 sc1
	ds_write_b16 v150, v156 offset:9216
	ds_write_b16_d16_hi v150, v156 offset:9360
	ds_write_b16 v150, v157 offset:9504
	ds_write_b16_d16_hi v150, v157 offset:9648
	v_pk_mul_f32 v[156:157], v[52:53], v[158:159]
	v_pk_mul_f32 v[158:159], v[54:55], v[160:161]
	v_add_f32_e32 v129, 1.0, v129
	v_cvt_pk_bf16_f32 v156, v156, v157
	v_cvt_pk_bf16_f32 v157, v158, v159
	v_rcp_f32_e32 v158, v129
	v_add_f32_e32 v129, 1.0, v135
	v_mul_f32_e32 v135, 0x3d372713, v58
	v_mul_f32_e32 v135, v58, v135
	v_mul_f32_e32 v137, 0x3d372713, v59
	v_fma_f32 v135, v58, v135, v58
	v_mul_f32_e32 v137, v59, v137
	v_mul_f32_e32 v135, 0x3fcc422a, v135
	v_fma_f32 v137, v59, v137, v59
	v_mul_f32_e32 v135, 0xbfb8aa3b, v135
	v_mul_f32_e32 v137, 0x3fcc422a, v137
	v_exp_f32_e32 v135, v135
	v_mul_f32_e32 v137, 0xbfb8aa3b, v137
	v_exp_f32_e32 v137, v137
	v_rcp_f32_e32 v159, v129
	v_add_f32_e32 v129, 1.0, v135
	v_rcp_f32_e32 v160, v129
	v_add_f32_e32 v129, 1.0, v137
	v_rcp_f32_e32 v161, v129
	v_mul_f32_e32 v129, 0x3d372713, v48
	v_mul_f32_e32 v129, v48, v129
	v_mul_f32_e32 v135, 0x3d372713, v49
	v_fma_f32 v129, v48, v129, v48
	v_mul_f32_e32 v135, v49, v135
	v_mul_f32_e32 v129, 0x3fcc422a, v129
	v_fma_f32 v135, v49, v135, v49
	v_mul_f32_e32 v129, 0xbfb8aa3b, v129
	v_mul_f32_e32 v135, 0x3fcc422a, v135
	v_exp_f32_e32 v129, v129
	v_mul_f32_e32 v135, 0xbfb8aa3b, v135
	v_exp_f32_e32 v135, v135
	global_store_dwordx2 v[138:139], v[156:157], off offset:128 sc1
	ds_write_b16 v150, v156 offset:9248
	ds_write_b16_d16_hi v150, v156 offset:9392
	ds_write_b16 v150, v157 offset:9536
	ds_write_b16_d16_hi v150, v157 offset:9680
	v_pk_mul_f32 v[156:157], v[56:57], v[158:159]
	v_pk_mul_f32 v[158:159], v[58:59], v[160:161]
	v_add_f32_e32 v129, 1.0, v129
	v_cvt_pk_bf16_f32 v156, v156, v157
	v_cvt_pk_bf16_f32 v157, v158, v159
	v_rcp_f32_e32 v158, v129
	v_add_f32_e32 v129, 1.0, v135
	v_mul_f32_e32 v135, 0x3d372713, v50
	v_mul_f32_e32 v135, v50, v135
	v_mul_f32_e32 v137, 0x3d372713, v51
	v_fma_f32 v135, v50, v135, v50
	v_mul_f32_e32 v137, v51, v137
	v_mul_f32_e32 v135, 0x3fcc422a, v135
	v_fma_f32 v137, v51, v137, v51
	v_mul_f32_e32 v135, 0xbfb8aa3b, v135
	v_mul_f32_e32 v137, 0x3fcc422a, v137
	v_exp_f32_e32 v135, v135
	v_mul_f32_e32 v137, 0xbfb8aa3b, v137
	v_exp_f32_e32 v137, v137
	v_rcp_f32_e32 v159, v129
	v_add_f32_e32 v129, 1.0, v135
	v_rcp_f32_e32 v160, v129
	v_add_f32_e32 v129, 1.0, v137
	v_rcp_f32_e32 v161, v129
	v_mul_f32_e32 v129, 0x3d372713, v44
	v_mul_f32_e32 v129, v44, v129
	v_mul_f32_e32 v135, 0x3d372713, v45
	v_fma_f32 v129, v44, v129, v44
	v_mul_f32_e32 v135, v45, v135
	v_mul_f32_e32 v129, 0x3fcc422a, v129
	v_fma_f32 v135, v45, v135, v45
	v_mul_f32_e32 v129, 0xbfb8aa3b, v129
	v_mul_f32_e32 v135, 0x3fcc422a, v135
	v_exp_f32_e32 v129, v129
	v_mul_f32_e32 v135, 0xbfb8aa3b, v135
	v_exp_f32_e32 v135, v135
	global_store_dwordx2 v[142:143], v[156:157], off offset:128 sc1
	ds_write_b16 v150, v156 offset:9280
	ds_write_b16_d16_hi v150, v156 offset:9424
	ds_write_b16 v150, v157 offset:9568
	ds_write_b16_d16_hi v150, v157 offset:9712
	v_pk_mul_f32 v[156:157], v[48:49], v[158:159]
	v_pk_mul_f32 v[158:159], v[50:51], v[160:161]
	v_add_f32_e32 v129, 1.0, v129
	v_cvt_pk_bf16_f32 v156, v156, v157
	v_cvt_pk_bf16_f32 v157, v158, v159
	v_rcp_f32_e32 v158, v129
	v_add_f32_e32 v129, 1.0, v135
	v_mul_f32_e32 v135, 0x3d372713, v46
	v_mul_f32_e32 v135, v46, v135
	v_mul_f32_e32 v137, 0x3d372713, v47
	v_fma_f32 v135, v46, v135, v46
	v_mul_f32_e32 v137, v47, v137
	v_mul_f32_e32 v135, 0x3fcc422a, v135
	v_fma_f32 v137, v47, v137, v47
	v_mul_f32_e32 v135, 0xbfb8aa3b, v135
	v_mul_f32_e32 v137, 0x3fcc422a, v137
	v_exp_f32_e32 v135, v135
	v_mul_f32_e32 v137, 0xbfb8aa3b, v137
	v_exp_f32_e32 v137, v137
	v_rcp_f32_e32 v159, v129
	v_add_f32_e32 v129, 1.0, v135
	v_rcp_f32_e32 v160, v129
	v_add_f32_e32 v129, 1.0, v137
	v_rcp_f32_e32 v161, v129
	v_mul_f32_e32 v129, 0x3d372713, v36
	v_mul_f32_e32 v129, v36, v129
	v_mul_f32_e32 v135, 0x3d372713, v37
	v_fma_f32 v129, v36, v129, v36
	v_mul_f32_e32 v135, v37, v135
	v_mul_f32_e32 v129, 0x3fcc422a, v129
	v_fma_f32 v135, v37, v135, v37
	v_mul_f32_e32 v129, 0xbfb8aa3b, v129
	v_mul_f32_e32 v135, 0x3fcc422a, v135
	v_exp_f32_e32 v129, v129
	v_mul_f32_e32 v135, 0xbfb8aa3b, v135
	v_exp_f32_e32 v135, v135
	global_store_dwordx2 v[144:145], v[156:157], off offset:128 sc1
	ds_write_b16 v150, v156 offset:9312
	ds_write_b16_d16_hi v150, v156 offset:9456
	ds_write_b16 v150, v157 offset:9600
	ds_write_b16_d16_hi v150, v157 offset:9744
	v_pk_mul_f32 v[156:157], v[44:45], v[158:159]
	v_pk_mul_f32 v[158:159], v[46:47], v[160:161]
	v_add_f32_e32 v129, 1.0, v129
	v_cvt_pk_bf16_f32 v156, v156, v157
	v_cvt_pk_bf16_f32 v157, v158, v159
	v_rcp_f32_e32 v158, v129
	v_add_f32_e32 v129, 1.0, v135
	v_mul_f32_e32 v135, 0x3d372713, v38
	v_mul_f32_e32 v135, v38, v135
	v_mul_f32_e32 v137, 0x3d372713, v39
	v_fma_f32 v135, v38, v135, v38
	v_mul_f32_e32 v137, v39, v137
	v_mul_f32_e32 v135, 0x3fcc422a, v135
	v_fma_f32 v137, v39, v137, v39
	v_mul_f32_e32 v135, 0xbfb8aa3b, v135
	v_mul_f32_e32 v137, 0x3fcc422a, v137
	v_exp_f32_e32 v135, v135
	v_mul_f32_e32 v137, 0xbfb8aa3b, v137
	v_exp_f32_e32 v137, v137
	v_rcp_f32_e32 v159, v129
	v_add_f32_e32 v129, 1.0, v135
	v_rcp_f32_e32 v160, v129
	v_add_f32_e32 v129, 1.0, v137
	v_rcp_f32_e32 v161, v129
	v_mul_f32_e32 v129, 0x3d372713, v40
	v_mul_f32_e32 v129, v40, v129
	v_mul_f32_e32 v135, 0x3d372713, v41
	v_fma_f32 v129, v40, v129, v40
	v_mul_f32_e32 v135, v41, v135
	v_mul_f32_e32 v129, 0x3fcc422a, v129
	v_fma_f32 v135, v41, v135, v41
	v_mul_f32_e32 v129, 0xbfb8aa3b, v129
	v_mul_f32_e32 v135, 0x3fcc422a, v135
	v_exp_f32_e32 v129, v129
	v_mul_f32_e32 v135, 0xbfb8aa3b, v135
	v_exp_f32_e32 v135, v135
	global_store_dwordx2 v[140:141], v[156:157], off offset:160 sc1
	ds_write_b16 v150, v156 offset:11520
	ds_write_b16_d16_hi v150, v156 offset:11664
	ds_write_b16 v150, v157 offset:11808
	ds_write_b16_d16_hi v150, v157 offset:11952
	v_pk_mul_f32 v[156:157], v[36:37], v[158:159]
	v_pk_mul_f32 v[158:159], v[38:39], v[160:161]
	v_add_f32_e32 v129, 1.0, v129
	v_cvt_pk_bf16_f32 v156, v156, v157
	v_cvt_pk_bf16_f32 v157, v158, v159
	v_rcp_f32_e32 v158, v129
	v_add_f32_e32 v129, 1.0, v135
	v_mul_f32_e32 v135, 0x3d372713, v42
	v_mul_f32_e32 v135, v42, v135
	v_mul_f32_e32 v137, 0x3d372713, v43
	v_fma_f32 v135, v42, v135, v42
	v_mul_f32_e32 v137, v43, v137
	v_mul_f32_e32 v135, 0x3fcc422a, v135
	v_fma_f32 v137, v43, v137, v43
	v_mul_f32_e32 v135, 0xbfb8aa3b, v135
	v_mul_f32_e32 v137, 0x3fcc422a, v137
	v_exp_f32_e32 v135, v135
	v_mul_f32_e32 v137, 0xbfb8aa3b, v137
	v_exp_f32_e32 v137, v137
	v_rcp_f32_e32 v159, v129
	v_add_f32_e32 v129, 1.0, v135
	v_rcp_f32_e32 v160, v129
	v_add_f32_e32 v129, 1.0, v137
	v_rcp_f32_e32 v161, v129
	v_mul_f32_e32 v129, 0x3d372713, v32
	v_mul_f32_e32 v129, v32, v129
	v_mul_f32_e32 v135, 0x3d372713, v33
	v_fma_f32 v129, v32, v129, v32
	v_mul_f32_e32 v135, v33, v135
	v_mul_f32_e32 v129, 0x3fcc422a, v129
	v_fma_f32 v135, v33, v135, v33
	v_mul_f32_e32 v129, 0xbfb8aa3b, v129
	v_mul_f32_e32 v135, 0x3fcc422a, v135
	v_exp_f32_e32 v129, v129
	v_mul_f32_e32 v135, 0xbfb8aa3b, v135
	v_exp_f32_e32 v135, v135
	global_store_dwordx2 v[138:139], v[156:157], off offset:160 sc1
	ds_write_b16 v150, v156 offset:11552
	ds_write_b16_d16_hi v150, v156 offset:11696
	ds_write_b16 v150, v157 offset:11840
	ds_write_b16_d16_hi v150, v157 offset:11984
	v_pk_mul_f32 v[156:157], v[40:41], v[158:159]
	v_pk_mul_f32 v[158:159], v[42:43], v[160:161]
	v_add_f32_e32 v129, 1.0, v129
	v_cvt_pk_bf16_f32 v156, v156, v157
	v_cvt_pk_bf16_f32 v157, v158, v159
	v_rcp_f32_e32 v158, v129
	v_add_f32_e32 v129, 1.0, v135
	v_mul_f32_e32 v135, 0x3d372713, v34
	v_mul_f32_e32 v135, v34, v135
	v_mul_f32_e32 v137, 0x3d372713, v35
	v_fma_f32 v135, v34, v135, v34
	v_mul_f32_e32 v137, v35, v137
	v_mul_f32_e32 v135, 0x3fcc422a, v135
	v_fma_f32 v137, v35, v137, v35
	v_mul_f32_e32 v135, 0xbfb8aa3b, v135
	v_mul_f32_e32 v137, 0x3fcc422a, v137
	v_exp_f32_e32 v135, v135
	v_mul_f32_e32 v137, 0xbfb8aa3b, v137
	v_exp_f32_e32 v137, v137
	v_rcp_f32_e32 v159, v129
	v_add_f32_e32 v129, 1.0, v135
	v_rcp_f32_e32 v160, v129
	v_add_f32_e32 v129, 1.0, v137
	v_rcp_f32_e32 v161, v129
	v_mul_f32_e32 v129, 0x3d372713, v28
	v_mul_f32_e32 v129, v28, v129
	v_mul_f32_e32 v135, 0x3d372713, v29
	v_fma_f32 v129, v28, v129, v28
	v_mul_f32_e32 v135, v29, v135
	v_mul_f32_e32 v129, 0x3fcc422a, v129
	v_fma_f32 v135, v29, v135, v29
	v_mul_f32_e32 v129, 0xbfb8aa3b, v129
	v_mul_f32_e32 v135, 0x3fcc422a, v135
	v_exp_f32_e32 v129, v129
	v_mul_f32_e32 v135, 0xbfb8aa3b, v135
	v_exp_f32_e32 v135, v135
	global_store_dwordx2 v[142:143], v[156:157], off offset:160 sc1
	ds_write_b16 v150, v156 offset:11584
	ds_write_b16_d16_hi v150, v156 offset:11728
	ds_write_b16 v150, v157 offset:11872
	ds_write_b16_d16_hi v150, v157 offset:12016
	v_pk_mul_f32 v[156:157], v[32:33], v[158:159]
	v_pk_mul_f32 v[158:159], v[34:35], v[160:161]
	v_add_f32_e32 v129, 1.0, v129
	v_cvt_pk_bf16_f32 v156, v156, v157
	v_cvt_pk_bf16_f32 v157, v158, v159
	v_rcp_f32_e32 v158, v129
	v_add_f32_e32 v129, 1.0, v135
	v_mul_f32_e32 v135, 0x3d372713, v30
	v_mul_f32_e32 v135, v30, v135
	v_mul_f32_e32 v137, 0x3d372713, v31
	v_fma_f32 v135, v30, v135, v30
	v_mul_f32_e32 v137, v31, v137
	v_mul_f32_e32 v135, 0x3fcc422a, v135
	v_fma_f32 v137, v31, v137, v31
	v_mul_f32_e32 v135, 0xbfb8aa3b, v135
	v_mul_f32_e32 v137, 0x3fcc422a, v137
	v_exp_f32_e32 v135, v135
	v_mul_f32_e32 v137, 0xbfb8aa3b, v137
	v_exp_f32_e32 v137, v137
	v_rcp_f32_e32 v159, v129
	v_add_f32_e32 v129, 1.0, v135
	v_rcp_f32_e32 v160, v129
	v_add_f32_e32 v129, 1.0, v137
	v_rcp_f32_e32 v161, v129
	v_mul_f32_e32 v129, 0x3d372713, v16
	v_mul_f32_e32 v129, v16, v129
	v_mul_f32_e32 v135, 0x3d372713, v17
	v_fma_f32 v129, v16, v129, v16
	v_mul_f32_e32 v135, v17, v135
	v_mul_f32_e32 v129, 0x3fcc422a, v129
	v_fma_f32 v135, v17, v135, v17
	v_mul_f32_e32 v129, 0xbfb8aa3b, v129
	v_mul_f32_e32 v135, 0x3fcc422a, v135
	v_exp_f32_e32 v129, v129
	v_mul_f32_e32 v135, 0xbfb8aa3b, v135
	v_exp_f32_e32 v135, v135
	global_store_dwordx2 v[144:145], v[156:157], off offset:160 sc1
	ds_write_b16 v150, v156 offset:11616
	ds_write_b16_d16_hi v150, v156 offset:11760
	ds_write_b16 v150, v157 offset:11904
	ds_write_b16_d16_hi v150, v157 offset:12048
	v_pk_mul_f32 v[156:157], v[28:29], v[158:159]
	v_pk_mul_f32 v[158:159], v[30:31], v[160:161]
	v_add_f32_e32 v129, 1.0, v129
	v_cvt_pk_bf16_f32 v156, v156, v157
	v_cvt_pk_bf16_f32 v157, v158, v159
	v_rcp_f32_e32 v158, v129
	v_add_f32_e32 v129, 1.0, v135
	v_mul_f32_e32 v135, 0x3d372713, v18
	v_mul_f32_e32 v135, v18, v135
	v_mul_f32_e32 v137, 0x3d372713, v19
	v_fma_f32 v135, v18, v135, v18
	v_mul_f32_e32 v137, v19, v137
	v_mul_f32_e32 v135, 0x3fcc422a, v135
	v_fma_f32 v137, v19, v137, v19
	v_mul_f32_e32 v135, 0xbfb8aa3b, v135
	v_mul_f32_e32 v137, 0x3fcc422a, v137
	v_exp_f32_e32 v135, v135
	v_mul_f32_e32 v137, 0xbfb8aa3b, v137
	v_exp_f32_e32 v137, v137
	v_rcp_f32_e32 v159, v129
	v_add_f32_e32 v129, 1.0, v135
	v_rcp_f32_e32 v160, v129
	v_add_f32_e32 v129, 1.0, v137
	v_rcp_f32_e32 v161, v129
	v_mul_f32_e32 v129, 0x3d372713, v24
	v_mul_f32_e32 v129, v24, v129
	v_mul_f32_e32 v135, 0x3d372713, v25
	v_fma_f32 v129, v24, v129, v24
	v_mul_f32_e32 v135, v25, v135
	v_mul_f32_e32 v129, 0x3fcc422a, v129
	v_fma_f32 v135, v25, v135, v25
	v_mul_f32_e32 v129, 0xbfb8aa3b, v129
	v_mul_f32_e32 v135, 0x3fcc422a, v135
	v_exp_f32_e32 v129, v129
	v_mul_f32_e32 v135, 0xbfb8aa3b, v135
	v_exp_f32_e32 v135, v135
	global_store_dwordx2 v[140:141], v[156:157], off offset:192 sc1
	ds_write_b16 v150, v156 offset:13824
	ds_write_b16_d16_hi v150, v156 offset:13968
	ds_write_b16 v150, v157 offset:14112
	ds_write_b16_d16_hi v150, v157 offset:14256
	v_pk_mul_f32 v[156:157], v[16:17], v[158:159]
	v_pk_mul_f32 v[158:159], v[18:19], v[160:161]
	v_add_f32_e32 v129, 1.0, v129
	v_cvt_pk_bf16_f32 v156, v156, v157
	v_cvt_pk_bf16_f32 v157, v158, v159
	v_rcp_f32_e32 v158, v129
	v_add_f32_e32 v129, 1.0, v135
	v_mul_f32_e32 v135, 0x3d372713, v26
	v_mul_f32_e32 v135, v26, v135
	v_mul_f32_e32 v137, 0x3d372713, v27
	v_fma_f32 v135, v26, v135, v26
	v_mul_f32_e32 v137, v27, v137
	v_mul_f32_e32 v135, 0x3fcc422a, v135
	v_fma_f32 v137, v27, v137, v27
	v_mul_f32_e32 v135, 0xbfb8aa3b, v135
	v_mul_f32_e32 v137, 0x3fcc422a, v137
	v_exp_f32_e32 v135, v135
	v_mul_f32_e32 v137, 0xbfb8aa3b, v137
	v_exp_f32_e32 v137, v137
	v_rcp_f32_e32 v159, v129
	v_add_f32_e32 v129, 1.0, v135
	v_rcp_f32_e32 v160, v129
	v_add_f32_e32 v129, 1.0, v137
	v_rcp_f32_e32 v161, v129
	v_mul_f32_e32 v129, 0x3d372713, v12
	v_mul_f32_e32 v129, v12, v129
	v_mul_f32_e32 v135, 0x3d372713, v13
	v_fma_f32 v129, v12, v129, v12
	v_mul_f32_e32 v135, v13, v135
	v_mul_f32_e32 v129, 0x3fcc422a, v129
	v_fma_f32 v135, v13, v135, v13
	v_mul_f32_e32 v129, 0xbfb8aa3b, v129
	v_mul_f32_e32 v135, 0x3fcc422a, v135
	v_exp_f32_e32 v129, v129
	v_mul_f32_e32 v135, 0xbfb8aa3b, v135
	v_exp_f32_e32 v135, v135
	global_store_dwordx2 v[138:139], v[156:157], off offset:192 sc1
	ds_write_b16 v150, v156 offset:13856
	ds_write_b16_d16_hi v150, v156 offset:14000
	ds_write_b16 v150, v157 offset:14144
	ds_write_b16_d16_hi v150, v157 offset:14288
	v_pk_mul_f32 v[156:157], v[24:25], v[158:159]
	v_pk_mul_f32 v[158:159], v[26:27], v[160:161]
	v_add_f32_e32 v129, 1.0, v129
	v_cvt_pk_bf16_f32 v156, v156, v157
	v_cvt_pk_bf16_f32 v157, v158, v159
	v_rcp_f32_e32 v158, v129
	v_add_f32_e32 v129, 1.0, v135
	v_mul_f32_e32 v135, 0x3d372713, v14
	v_mul_f32_e32 v135, v14, v135
	v_mul_f32_e32 v137, 0x3d372713, v15
	v_fma_f32 v135, v14, v135, v14
	v_mul_f32_e32 v137, v15, v137
	v_mul_f32_e32 v135, 0x3fcc422a, v135
	v_fma_f32 v137, v15, v137, v15
	v_mul_f32_e32 v135, 0xbfb8aa3b, v135
	v_mul_f32_e32 v137, 0x3fcc422a, v137
	v_exp_f32_e32 v135, v135
	v_mul_f32_e32 v137, 0xbfb8aa3b, v137
	v_exp_f32_e32 v137, v137
	v_rcp_f32_e32 v159, v129
	v_add_f32_e32 v129, 1.0, v135
	v_rcp_f32_e32 v160, v129
	v_add_f32_e32 v129, 1.0, v137
	v_rcp_f32_e32 v161, v129
	v_mul_f32_e32 v129, 0x3d372713, v4
	v_mul_f32_e32 v129, v4, v129
	v_mul_f32_e32 v135, 0x3d372713, v5
	v_fma_f32 v129, v4, v129, v4
	v_mul_f32_e32 v135, v5, v135
	v_mul_f32_e32 v129, 0x3fcc422a, v129
	v_fma_f32 v135, v5, v135, v5
	v_mul_f32_e32 v129, 0xbfb8aa3b, v129
	v_mul_f32_e32 v135, 0x3fcc422a, v135
	v_exp_f32_e32 v129, v129
	v_mul_f32_e32 v135, 0xbfb8aa3b, v135
	v_exp_f32_e32 v135, v135
	global_store_dwordx2 v[142:143], v[156:157], off offset:192 sc1
	ds_write_b16 v150, v156 offset:13888
	ds_write_b16_d16_hi v150, v156 offset:14032
	ds_write_b16 v150, v157 offset:14176
	ds_write_b16_d16_hi v150, v157 offset:14320
	v_pk_mul_f32 v[156:157], v[12:13], v[158:159]
	v_pk_mul_f32 v[158:159], v[14:15], v[160:161]
	v_add_f32_e32 v129, 1.0, v129
	v_cvt_pk_bf16_f32 v156, v156, v157
	v_cvt_pk_bf16_f32 v157, v158, v159
	v_rcp_f32_e32 v158, v129
	v_add_f32_e32 v129, 1.0, v135
	v_mul_f32_e32 v135, 0x3d372713, v6
	v_mul_f32_e32 v135, v6, v135
	v_mul_f32_e32 v137, 0x3d372713, v7
	v_fma_f32 v135, v6, v135, v6
	v_mul_f32_e32 v137, v7, v137
	v_mul_f32_e32 v135, 0x3fcc422a, v135
	v_fma_f32 v137, v7, v137, v7
	v_mul_f32_e32 v135, 0xbfb8aa3b, v135
	v_mul_f32_e32 v137, 0x3fcc422a, v137
	v_exp_f32_e32 v135, v135
	v_mul_f32_e32 v137, 0xbfb8aa3b, v137
	v_exp_f32_e32 v137, v137
	v_rcp_f32_e32 v159, v129
	v_add_f32_e32 v129, 1.0, v135
	v_rcp_f32_e32 v160, v129
	v_add_f32_e32 v129, 1.0, v137
	v_rcp_f32_e32 v161, v129
	v_mul_f32_e32 v129, 0x3d372713, v0
	v_mul_f32_e32 v129, v0, v129
	v_mul_f32_e32 v135, 0x3d372713, v1
	v_fma_f32 v129, v0, v129, v0
	v_mul_f32_e32 v135, v1, v135
	v_mul_f32_e32 v129, 0x3fcc422a, v129
	v_fma_f32 v135, v1, v135, v1
	v_mul_f32_e32 v129, 0xbfb8aa3b, v129
	v_mul_f32_e32 v135, 0x3fcc422a, v135
	v_exp_f32_e32 v129, v129
	v_mul_f32_e32 v135, 0xbfb8aa3b, v135
	v_exp_f32_e32 v135, v135
	global_store_dwordx2 v[144:145], v[156:157], off offset:192 sc1
	ds_write_b16 v150, v156 offset:13920
	ds_write_b16_d16_hi v150, v156 offset:14064
	ds_write_b16 v150, v157 offset:14208
	ds_write_b16_d16_hi v150, v157 offset:14352
	v_pk_mul_f32 v[156:157], v[4:5], v[158:159]
	v_pk_mul_f32 v[158:159], v[6:7], v[160:161]
	v_cvt_pk_bf16_f32 v156, v156, v157
	v_cvt_pk_bf16_f32 v157, v158, v159
	v_add_f32_e32 v129, 1.0, v129
	global_store_dwordx2 v[140:141], v[156:157], off offset:224 sc1
	v_rcp_f32_e32 v140, v129
	v_add_f32_e32 v129, 1.0, v135
	v_mul_f32_e32 v135, 0x3d372713, v2
	v_mul_f32_e32 v135, v2, v135
	v_mul_f32_e32 v137, 0x3d372713, v3
	v_fma_f32 v135, v2, v135, v2
	v_mul_f32_e32 v137, v3, v137
	v_mul_f32_e32 v135, 0x3fcc422a, v135
	v_fma_f32 v137, v3, v137, v3
	v_mul_f32_e32 v135, 0xbfb8aa3b, v135
	v_mul_f32_e32 v137, 0x3fcc422a, v137
	v_exp_f32_e32 v135, v135
	v_mul_f32_e32 v137, 0xbfb8aa3b, v137
	v_exp_f32_e32 v137, v137
	v_rcp_f32_e32 v141, v129
	v_add_f32_e32 v129, 1.0, v135
	v_rcp_f32_e32 v158, v129
	v_add_f32_e32 v129, 1.0, v137
	v_rcp_f32_e32 v159, v129
	v_mul_f32_e32 v129, 0x3d372713, v20
	v_mul_f32_e32 v129, v20, v129
	v_mul_f32_e32 v135, 0x3d372713, v21
	v_fma_f32 v129, v20, v129, v20
	v_mul_f32_e32 v135, v21, v135
	v_mul_f32_e32 v129, 0x3fcc422a, v129
	v_fma_f32 v135, v21, v135, v21
	v_mul_f32_e32 v129, 0xbfb8aa3b, v129
	v_mul_f32_e32 v135, 0x3fcc422a, v135
	v_exp_f32_e32 v129, v129
	v_mul_f32_e32 v135, 0xbfb8aa3b, v135
	v_exp_f32_e32 v135, v135
	ds_write_b16 v150, v156 offset:16128
	ds_write_b16_d16_hi v150, v156 offset:16272
	ds_write_b16 v150, v157 offset:16416
	ds_write_b16_d16_hi v150, v157 offset:16560
	v_pk_mul_f32 v[140:141], v[0:1], v[140:141]
	v_pk_mul_f32 v[156:157], v[2:3], v[158:159]
	v_cvt_pk_bf16_f32 v140, v140, v141
	v_cvt_pk_bf16_f32 v141, v156, v157
	v_add_f32_e32 v129, 1.0, v129
	global_store_dwordx2 v[138:139], v[140:141], off offset:224 sc1
	v_rcp_f32_e32 v138, v129
	v_add_f32_e32 v129, 1.0, v135
	v_mul_f32_e32 v135, 0x3d372713, v22
	v_mul_f32_e32 v135, v22, v135
	v_mul_f32_e32 v137, 0x3d372713, v23
	v_fma_f32 v135, v22, v135, v22
	v_mul_f32_e32 v137, v23, v137
	v_mul_f32_e32 v135, 0x3fcc422a, v135
	v_fma_f32 v137, v23, v137, v23
	v_mul_f32_e32 v135, 0xbfb8aa3b, v135
	v_mul_f32_e32 v137, 0x3fcc422a, v137
	v_exp_f32_e32 v135, v135
	v_mul_f32_e32 v137, 0xbfb8aa3b, v137
	v_exp_f32_e32 v137, v137
	v_rcp_f32_e32 v139, v129
	v_add_f32_e32 v129, 1.0, v135
	v_rcp_f32_e32 v156, v129
	v_add_f32_e32 v129, 1.0, v137
	v_rcp_f32_e32 v157, v129
	v_mul_f32_e32 v129, 0x3d372713, v8
	v_mul_f32_e32 v129, v8, v129
	v_mul_f32_e32 v135, 0x3d372713, v9
	v_fma_f32 v129, v8, v129, v8
	v_mul_f32_e32 v135, v9, v135
	v_mul_f32_e32 v129, 0x3fcc422a, v129
	v_fma_f32 v135, v9, v135, v9
	v_mul_f32_e32 v129, 0xbfb8aa3b, v129
	v_mul_f32_e32 v135, 0x3fcc422a, v135
	v_exp_f32_e32 v129, v129
	v_mul_f32_e32 v135, 0xbfb8aa3b, v135
	v_exp_f32_e32 v135, v135
	ds_write_b16 v150, v140 offset:16160
	ds_write_b16_d16_hi v150, v140 offset:16304
	ds_write_b16 v150, v141 offset:16448
	ds_write_b16_d16_hi v150, v141 offset:16592
	v_pk_mul_f32 v[138:139], v[20:21], v[138:139]
	v_pk_mul_f32 v[140:141], v[22:23], v[156:157]
	v_add_f32_e32 v129, 1.0, v129
	v_cvt_pk_bf16_f32 v138, v138, v139
	v_cvt_pk_bf16_f32 v139, v140, v141
	v_rcp_f32_e32 v140, v129
	v_add_f32_e32 v129, 1.0, v135
	v_mul_f32_e32 v135, 0x3d372713, v10
	v_mul_f32_e32 v135, v10, v135
	v_mul_f32_e32 v137, 0x3d372713, v11
	v_fma_f32 v135, v10, v135, v10
	v_mul_f32_e32 v137, v11, v137
	v_mul_f32_e32 v135, 0x3fcc422a, v135
	v_fma_f32 v137, v11, v137, v11
	v_mul_f32_e32 v135, 0xbfb8aa3b, v135
	v_mul_f32_e32 v137, 0x3fcc422a, v137
	v_exp_f32_e32 v135, v135
	v_mul_f32_e32 v137, 0xbfb8aa3b, v137
	v_exp_f32_e32 v137, v137
	v_rcp_f32_e32 v141, v129
	v_add_f32_e32 v129, 1.0, v135
	global_store_dwordx2 v[142:143], v[138:139], off offset:224 sc1
	v_rcp_f32_e32 v142, v129
	v_add_f32_e32 v129, 1.0, v137
	v_rcp_f32_e32 v143, v129
	v_and_b32_e32 v135, 64, v154
	v_xor_b32_e32 v129, 1, v154
	v_add_u32_e32 v135, 64, v135
	v_cmp_lt_i32_e32 vcc, v129, v135
	ds_write_b16 v150, v138 offset:16192
	ds_write_b16_d16_hi v150, v138 offset:16336
	v_cndmask_b32_e32 v129, v154, v129, vcc
	ds_write_b16 v150, v139 offset:16480
	ds_write_b16_d16_hi v150, v139 offset:16624
	v_pk_mul_f32 v[138:139], v[8:9], v[140:141]
	v_pk_mul_f32 v[140:141], v[10:11], v[142:143]
	v_lshlrev_b32_e32 v142, 2, v129
	v_xor_b32_e32 v129, 2, v154
	v_cmp_lt_i32_e32 vcc, v129, v135
	v_cvt_pk_bf16_f32 v138, v138, v139
	v_cvt_pk_bf16_f32 v139, v140, v141
	v_cndmask_b32_e32 v129, v154, v129, vcc
	global_store_dwordx2 v[144:145], v[138:139], off offset:224 sc1
	ds_write_b16 v150, v138 offset:16224
	ds_write_b16_d16_hi v150, v138 offset:16368
	ds_write_b16 v150, v139 offset:16512
	ds_write_b16_d16_hi v150, v139 offset:16656
	v_lshlrev_b32_e32 v143, 2, v129
	v_xor_b32_e32 v129, 4, v154
	s_waitcnt lgkmcnt(0)
	v_cmp_lt_i32_e32 vcc, v129, v135
	v_mov_b32_e32 v137, v128
	v_add_u32_e32 v134, s88, v151
	v_cndmask_b32_e32 v129, v154, v129, vcc
	s_mov_b32 s86, 0
	v_lshlrev_b32_e32 v144, 2, v129
	v_lshl_add_u64 v[136:137], v[136:137], 3, s[8:9]
	s_branch .LBB0_123

.LBB0_123:
	v_add_u32_e32 v145, s86, v152
	s_waitcnt lgkmcnt(0)
	ds_read_b128 v[138:141], v145
	s_waitcnt lgkmcnt(0)
	v_lshlrev_b32_e32 v157, 16, v138
	v_and_b32_e32 v156, 0xffff0000, v138
	v_lshlrev_b32_e32 v138, 16, v139
	v_and_b32_e32 v158, 0xffff0000, v139
	v_pk_mul_f32 v[168:169], v[156:157], v[156:157]
	v_mul_f32_e32 v139, v138, v138
	v_mul_f32_e32 v159, v158, v158
	v_lshlrev_b32_e32 v160, 16, v140
	v_and_b32_e32 v162, 0xffff0000, v140
	v_add_f32_e32 v166, v157, v156
	v_mov_b32_e32 v167, v169
	v_mul_f32_e32 v129, v156, v156
	v_mul_f32_e32 v161, v160, v160
	v_mul_f32_e32 v163, v162, v162
	v_lshlrev_b32_e32 v140, 16, v141
	v_and_b32_e32 v164, 0xffff0000, v141
	v_pk_add_f32 v[156:157], v[166:167], v[128:129]
	v_pk_add_f32 v[138:139], v[138:139], v[158:159]
	v_mul_f32_e32 v141, v140, v140
	v_mul_f32_e32 v165, v164, v164
	v_pk_add_f32 v[138:139], v[156:157], v[138:139]
	v_pk_add_f32 v[156:157], v[160:161], v[162:163]
	v_pk_add_f32 v[140:141], v[140:141], v[164:165]
	v_pk_add_f32 v[138:139], v[138:139], v[156:157]
	s_nop 0
	v_pk_add_f32 v[138:139], v[138:139], v[140:141]
	ds_bpermute_b32 v140, v142, v138
	ds_bpermute_b32 v141, v142, v139
	s_waitcnt lgkmcnt(0)
	v_pk_add_f32 v[138:139], v[138:139], v[140:141]
	ds_bpermute_b32 v140, v143, v138
	ds_bpermute_b32 v141, v143, v139
	s_waitcnt lgkmcnt(0)
	v_pk_add_f32 v[138:139], v[138:139], v[140:141]
	ds_bpermute_b32 v140, v144, v138
	ds_bpermute_b32 v141, v144, v139
	s_and_saveexec_b64 s[60:61], s[4:5]
	s_cbranch_execz .LBB0_125
	v_ashrrev_i32_e32 v135, 31, v134
	v_lshlrev_b64 v[156:157], 8, v[134:135]
	v_lshl_add_u64 v[156:157], v[136:137], 0, v[156:157]
	s_waitcnt lgkmcnt(0)
	v_pk_add_f32 v[138:139], v[138:139], v[140:141]
	global_store_dwordx2 v[156:157], v[138:139], off sc1
.LBB0_125:
	s_or_b64 exec, exec, s[60:61]
	s_waitcnt lgkmcnt(0)
	ds_read_b128 v[138:141], v145 offset:1152
	s_waitcnt lgkmcnt(0)
	v_lshlrev_b32_e32 v157, 16, v138
	v_and_b32_e32 v156, 0xffff0000, v138
	v_lshlrev_b32_e32 v138, 16, v139
	v_and_b32_e32 v158, 0xffff0000, v139
	v_pk_mul_f32 v[168:169], v[156:157], v[156:157]
	v_mul_f32_e32 v139, v138, v138
	v_mul_f32_e32 v159, v158, v158
	v_lshlrev_b32_e32 v160, 16, v140
	v_and_b32_e32 v162, 0xffff0000, v140
	v_add_f32_e32 v166, v157, v156
	v_mov_b32_e32 v167, v169
	v_mul_f32_e32 v129, v156, v156
	v_mul_f32_e32 v161, v160, v160
	v_mul_f32_e32 v163, v162, v162
	v_lshlrev_b32_e32 v140, 16, v141
	v_and_b32_e32 v164, 0xffff0000, v141
	v_pk_add_f32 v[156:157], v[166:167], v[128:129]
	v_pk_add_f32 v[138:139], v[138:139], v[158:159]
	v_mul_f32_e32 v141, v140, v140
	v_mul_f32_e32 v165, v164, v164
	v_pk_add_f32 v[138:139], v[156:157], v[138:139]
	v_pk_add_f32 v[156:157], v[160:161], v[162:163]
	v_pk_add_f32 v[140:141], v[140:141], v[164:165]
	v_pk_add_f32 v[138:139], v[138:139], v[156:157]
	s_nop 0
	v_pk_add_f32 v[138:139], v[138:139], v[140:141]
	ds_bpermute_b32 v140, v142, v138
	ds_bpermute_b32 v141, v142, v139
	s_waitcnt lgkmcnt(0)
	v_pk_add_f32 v[138:139], v[138:139], v[140:141]
	ds_bpermute_b32 v140, v143, v138
	ds_bpermute_b32 v141, v143, v139
	s_waitcnt lgkmcnt(0)
	v_pk_add_f32 v[138:139], v[138:139], v[140:141]
	ds_bpermute_b32 v140, v144, v138
	ds_bpermute_b32 v141, v144, v139
	s_and_saveexec_b64 s[60:61], s[4:5]
	s_cbranch_execz .LBB0_122
	v_add_u32_e32 v156, 8, v134
	v_ashrrev_i32_e32 v157, 31, v156
	v_lshlrev_b64 v[156:157], 8, v[156:157]
	v_lshl_add_u64 v[156:157], v[136:137], 0, v[156:157]
	s_waitcnt lgkmcnt(0)
	v_pk_add_f32 v[138:139], v[138:139], v[140:141]
	global_store_dwordx2 v[156:157], v[138:139], off sc1
	s_branch .LBB0_122

.LBB0_1494:
	v_lshl_add_u32 v136, s42, 2, v147
	v_mul_f32_e32 v129, 0x3d372713, v124
	v_mul_f32_e32 v134, 0x3d372713, v125
	v_mul_f32_e32 v137, 0x3d372713, v126
	v_mul_f32_e32 v138, 0x3d372713, v127
	v_mul_f32_e32 v139, 0x3d372713, v116
	v_mul_f32_e32 v142, 0x3d372713, v117
	v_mul_f32_e32 v145, 0x3d372713, v118
	v_mul_f32_e32 v155, 0x3d372713, v119
	v_mul_f32_e32 v156, 0x3d372713, v108
	v_mul_f32_e32 v157, 0x3d372713, v109
	v_mul_f32_e32 v158, 0x3d372713, v110
	v_mul_f32_e32 v159, 0x3d372713, v111
	v_mul_f32_e32 v160, 0x3d372713, v100
	v_mul_f32_e32 v161, 0x3d372713, v101
	v_mul_f32_e32 v162, 0x3d372713, v102
	v_mul_f32_e32 v169, 0x3d372713, v103
	v_mul_f32_e32 v170, 0x3d372713, v92
	v_mul_f32_e32 v171, 0x3d372713, v93
	v_mul_f32_e32 v172, 0x3d372713, v94
	v_mul_f32_e32 v173, 0x3d372713, v95
	s_lshl_b32 s46, s56, 8
	v_cmp_lt_i32_e32 vcc, 63, v136
	v_mul_f32_e32 v135, v124, v129
	v_mul_f32_e32 v144, v125, v134
	v_mul_f32_e32 v141, v126, v137
	v_mul_f32_e32 v140, v127, v138
	v_mul_f32_e32 v143, v116, v139
	v_mul_f32_e32 v142, v117, v142
	v_mul_f32_e32 v139, v118, v145
	v_mul_f32_e32 v138, v119, v155
	v_mul_f32_e32 v168, v108, v156
	v_mul_f32_e32 v167, v109, v157
	v_mul_f32_e32 v166, v110, v158
	v_mul_f32_e32 v165, v111, v159
	v_mul_f32_e32 v164, v100, v160
	v_mul_f32_e32 v163, v101, v161
	v_mul_f32_e32 v162, v102, v162
	v_mul_f32_e32 v161, v103, v169
	v_mul_f32_e32 v160, v92, v170
	v_mul_f32_e32 v159, v93, v171
	v_mul_f32_e32 v158, v94, v172
	v_mul_f32_e32 v157, v95, v173
	v_mul_f32_e32 v156, 0x3d372713, v84
	v_mul_f32_e32 v155, 0x3d372713, v85
	v_mul_f32_e32 v137, 0x3d372713, v86
	v_mul_f32_e32 v129, 0x3d372713, v87
	s_and_saveexec_b64 s[20:21], vcc
	s_xor_b64 s[42:43], exec, s[20:21]
	s_cbranch_execz .LBB0_1502
	v_fma_f32 v135, v124, v135, v124
	v_mul_f32_e32 v135, 0x3fcc422a, v135
	v_fma_f32 v144, v125, v144, v125
	v_mul_f32_e32 v135, 0xbfb8aa3b, v135
	v_mul_f32_e32 v144, 0x3fcc422a, v144
	v_fma_f32 v141, v126, v141, v126
	v_exp_f32_e32 v135, v135
	v_mul_f32_e32 v144, 0xbfb8aa3b, v144
	v_mul_f32_e32 v141, 0x3fcc422a, v141
	v_fma_f32 v140, v127, v140, v127
	v_exp_f32_e32 v145, v144
	v_mul_f32_e32 v141, 0xbfb8aa3b, v141
	v_mul_f32_e32 v140, 0x3fcc422a, v140
	v_exp_f32_e32 v141, v141
	v_mul_f32_e32 v140, 0xbfb8aa3b, v140
	v_exp_f32_e32 v169, v140
	v_add_f32_e32 v135, 1.0, v135
	v_rcp_f32_e32 v144, v135
	v_add_f32_e32 v135, 1.0, v145
	v_rcp_f32_e32 v145, v135
	v_add_f32_e32 v135, 1.0, v141
	v_rcp_f32_e32 v140, v135
	v_add_f32_e32 v135, 1.0, v169
	v_rcp_f32_e32 v141, v135
	v_fma_f32 v135, v116, v143, v116
	v_lshl_add_u32 v172, s53, 1, v146
	v_mul_f32_e32 v135, 0x3fcc422a, v135
	v_fma_f32 v142, v117, v142, v117
	v_subrev_u32_e32 v136, 64, v136
	v_ashrrev_i32_e32 v173, 31, v172
	v_mul_f32_e32 v135, 0xbfb8aa3b, v135
	v_mul_f32_e32 v142, 0x3fcc422a, v142
	v_fma_f32 v139, v118, v139, v118
	v_lshl_or_b32 v170, v136, 6, v148
	v_lshlrev_b64 v[172:173], 19, v[172:173]
	v_pk_mul_f32 v[144:145], v[124:125], v[144:145]
	v_pk_mul_f32 v[140:141], v[126:127], v[140:141]
	v_mov_b32_e32 v171, v128
	v_exp_f32_e32 v135, v135
	v_mul_f32_e32 v142, 0xbfb8aa3b, v142
	v_mul_f32_e32 v139, 0x3fcc422a, v139
	v_fma_f32 v138, v119, v138, v119
	v_lshl_add_u64 v[172:173], v[130:131], 0, v[172:173]
	v_cvt_pk_bf16_f32 v144, v144, v145
	v_cvt_pk_bf16_f32 v145, v140, v141
	v_lshlrev_b64 v[140:141], 8, v[170:171]
	v_exp_f32_e32 v143, v142
	v_mul_f32_e32 v139, 0xbfb8aa3b, v139
	v_mul_f32_e32 v138, 0x3fcc422a, v138
	v_lshl_add_u64 v[140:141], v[172:173], 0, v[140:141]
	v_exp_f32_e32 v139, v139
	v_mul_f32_e32 v138, 0xbfb8aa3b, v138
	global_store_dwordx2 v[140:141], v[144:145], off sc1
	ds_write_b16 v150, v144
	ds_write_b16_d16_hi v150, v144 offset:144
	v_exp_f32_e32 v144, v138
	v_add_f32_e32 v135, 1.0, v135
	v_rcp_f32_e32 v142, v135
	v_add_f32_e32 v135, 1.0, v143
	v_rcp_f32_e32 v143, v135
	v_add_f32_e32 v135, 1.0, v139
	v_rcp_f32_e32 v138, v135
	v_add_f32_e32 v135, 1.0, v144
	v_rcp_f32_e32 v139, v135
	ds_write_b16 v150, v145 offset:288
	ds_write_b16_d16_hi v150, v145 offset:432
	v_or_b32_e32 v144, 16, v170
	v_pk_mul_f32 v[142:143], v[116:117], v[142:143]
	v_pk_mul_f32 v[138:139], v[118:119], v[138:139]
	v_mov_b32_e32 v145, v128
	v_cvt_pk_bf16_f32 v142, v142, v143
	v_cvt_pk_bf16_f32 v143, v138, v139
	v_lshlrev_b64 v[138:139], 8, v[144:145]
	v_lshl_add_u64 v[138:139], v[172:173], 0, v[138:139]
	v_mul_f32_e32 v135, 0x3d372713, v120
	global_store_dwordx2 v[138:139], v[142:143], off sc1
	ds_write_b16 v150, v142 offset:32
	ds_write_b16_d16_hi v150, v142 offset:176
	v_mul_f32_e32 v135, v120, v135
	v_mul_f32_e32 v142, 0x3d372713, v121
	v_fma_f32 v135, v120, v135, v120
	v_mul_f32_e32 v142, v121, v142
	v_mul_f32_e32 v135, 0x3fcc422a, v135
	v_fma_f32 v142, v121, v142, v121
	v_mul_f32_e32 v135, 0xbfb8aa3b, v135
	v_mul_f32_e32 v142, 0x3fcc422a, v142
	v_exp_f32_e32 v135, v135
	v_mul_f32_e32 v142, 0xbfb8aa3b, v142
	v_exp_f32_e32 v142, v142
	v_mul_f32_e32 v145, 0x3d372713, v123
	v_add_f32_e32 v135, 1.0, v135
	v_rcp_f32_e32 v144, v135
	v_add_f32_e32 v135, 1.0, v142
	v_mul_f32_e32 v142, 0x3d372713, v122
	v_mul_f32_e32 v142, v122, v142
	v_fma_f32 v142, v122, v142, v122
	v_mul_f32_e32 v145, v123, v145
	v_mul_f32_e32 v142, 0x3fcc422a, v142
	v_fma_f32 v145, v123, v145, v123
	v_mul_f32_e32 v142, 0xbfb8aa3b, v142
	v_mul_f32_e32 v145, 0x3fcc422a, v145
	v_exp_f32_e32 v142, v142
	v_mul_f32_e32 v145, 0xbfb8aa3b, v145
	v_exp_f32_e32 v169, v145
	v_rcp_f32_e32 v145, v135
	v_add_f32_e32 v135, 1.0, v142
	v_rcp_f32_e32 v174, v135
	v_add_f32_e32 v135, 1.0, v169
	v_rcp_f32_e32 v175, v135
	ds_write_b16 v150, v143 offset:320
	ds_write_b16_d16_hi v150, v143 offset:464
	v_or_b32_e32 v142, 32, v170
	v_mov_b32_e32 v143, v128
	v_pk_mul_f32 v[144:145], v[120:121], v[144:145]
	v_pk_mul_f32 v[174:175], v[122:123], v[174:175]
	v_lshlrev_b64 v[142:143], 8, v[142:143]
	v_cvt_pk_bf16_f32 v144, v144, v145
	v_cvt_pk_bf16_f32 v145, v174, v175
	v_lshl_add_u64 v[142:143], v[172:173], 0, v[142:143]
	v_mul_f32_e32 v135, 0x3d372713, v112
	global_store_dwordx2 v[142:143], v[144:145], off sc1
	ds_write_b16 v150, v144 offset:64
	ds_write_b16_d16_hi v150, v144 offset:208
	v_mul_f32_e32 v135, v112, v135
	v_mul_f32_e32 v144, 0x3d372713, v113
	v_fma_f32 v135, v112, v135, v112
	v_mul_f32_e32 v144, v113, v144
	v_mul_f32_e32 v135, 0x3fcc422a, v135
	v_fma_f32 v144, v113, v144, v113
	v_mul_f32_e32 v135, 0xbfb8aa3b, v135
	v_mul_f32_e32 v144, 0x3fcc422a, v144
	v_exp_f32_e32 v135, v135
	v_mul_f32_e32 v144, 0xbfb8aa3b, v144
	v_exp_f32_e32 v144, v144
	v_mul_f32_e32 v169, 0x3d372713, v115
	v_add_f32_e32 v135, 1.0, v135
	v_rcp_f32_e32 v174, v135
	v_add_f32_e32 v135, 1.0, v144
	v_mul_f32_e32 v144, 0x3d372713, v114
	v_mul_f32_e32 v144, v114, v144
	v_fma_f32 v144, v114, v144, v114
	v_mul_f32_e32 v169, v115, v169
	v_mul_f32_e32 v144, 0x3fcc422a, v144
	v_fma_f32 v169, v115, v169, v115
	v_mul_f32_e32 v144, 0xbfb8aa3b, v144
	v_mul_f32_e32 v169, 0x3fcc422a, v169
	v_exp_f32_e32 v144, v144
	v_mul_f32_e32 v169, 0xbfb8aa3b, v169
	v_exp_f32_e32 v169, v169
	v_rcp_f32_e32 v175, v135
	v_add_f32_e32 v135, 1.0, v144
	v_rcp_f32_e32 v176, v135
	v_add_f32_e32 v135, 1.0, v169
	v_rcp_f32_e32 v177, v135
	v_fma_f32 v135, v108, v168, v108
	v_mul_f32_e32 v135, 0x3fcc422a, v135
	v_fma_f32 v167, v109, v167, v109
	v_mul_f32_e32 v135, 0xbfb8aa3b, v135
	v_mul_f32_e32 v167, 0x3fcc422a, v167
	v_fma_f32 v166, v110, v166, v110
	v_exp_f32_e32 v135, v135
	v_mul_f32_e32 v167, 0xbfb8aa3b, v167
	v_mul_f32_e32 v166, 0x3fcc422a, v166
	v_fma_f32 v165, v111, v165, v111
	v_exp_f32_e32 v167, v167
	v_mul_f32_e32 v166, 0xbfb8aa3b, v166
	v_mul_f32_e32 v165, 0x3fcc422a, v165
	v_exp_f32_e32 v166, v166
	v_mul_f32_e32 v165, 0xbfb8aa3b, v165
	v_exp_f32_e32 v165, v165
	v_add_f32_e32 v135, 1.0, v135
	v_rcp_f32_e32 v168, v135
	v_add_f32_e32 v135, 1.0, v167
	v_rcp_f32_e32 v169, v135
	v_add_f32_e32 v135, 1.0, v166
	v_rcp_f32_e32 v166, v135
	v_add_f32_e32 v135, 1.0, v165
	v_rcp_f32_e32 v167, v135
	v_fma_f32 v135, v100, v164, v100
	v_mul_f32_e32 v135, 0x3fcc422a, v135
	v_fma_f32 v163, v101, v163, v101
	v_mul_f32_e32 v135, 0xbfb8aa3b, v135
	v_mul_f32_e32 v163, 0x3fcc422a, v163
	v_fma_f32 v162, v102, v162, v102
	v_exp_f32_e32 v135, v135
	v_mul_f32_e32 v163, 0xbfb8aa3b, v163
	v_mul_f32_e32 v162, 0x3fcc422a, v162
	v_fma_f32 v161, v103, v161, v103
	v_exp_f32_e32 v163, v163
	v_mul_f32_e32 v162, 0xbfb8aa3b, v162
	v_mul_f32_e32 v161, 0x3fcc422a, v161
	v_exp_f32_e32 v162, v162
	v_mul_f32_e32 v161, 0xbfb8aa3b, v161
	v_exp_f32_e32 v161, v161
	v_add_f32_e32 v135, 1.0, v135
	v_rcp_f32_e32 v164, v135
	v_add_f32_e32 v135, 1.0, v163
	v_rcp_f32_e32 v165, v135
	v_add_f32_e32 v135, 1.0, v162
	v_rcp_f32_e32 v162, v135
	v_add_f32_e32 v135, 1.0, v161
	v_rcp_f32_e32 v163, v135
	v_mul_f32_e32 v135, 0x3d372713, v104
	v_mul_f32_e32 v135, v104, v135
	v_mul_f32_e32 v161, 0x3d372713, v105
	v_fma_f32 v135, v104, v135, v104
	v_mul_f32_e32 v161, v105, v161
	v_mul_f32_e32 v135, 0x3fcc422a, v135
	v_fma_f32 v161, v105, v161, v105
	v_mul_f32_e32 v135, 0xbfb8aa3b, v135
	v_mul_f32_e32 v161, 0x3fcc422a, v161
	v_exp_f32_e32 v135, v135
	v_mul_f32_e32 v161, 0xbfb8aa3b, v161
	v_exp_f32_e32 v161, v161
	v_pk_mul_f32 v[164:165], v[100:101], v[164:165]
	v_pk_mul_f32 v[162:163], v[102:103], v[162:163]
	v_add_f32_e32 v135, 1.0, v135
	v_cvt_pk_bf16_f32 v164, v164, v165
	v_cvt_pk_bf16_f32 v165, v162, v163
	v_rcp_f32_e32 v162, v135
	v_add_f32_e32 v135, 1.0, v161
	v_mul_f32_e32 v161, 0x3d372713, v106
	v_mul_f32_e32 v161, v106, v161
	v_mul_f32_e32 v163, 0x3d372713, v107
	v_fma_f32 v161, v106, v161, v106
	v_mul_f32_e32 v163, v107, v163
	ds_write_b16 v150, v145 offset:352
	ds_write_b16_d16_hi v150, v145 offset:496
	v_or_b32_e32 v144, 48, v170
	v_mov_b32_e32 v145, v128
	v_mul_f32_e32 v161, 0x3fcc422a, v161
	v_fma_f32 v163, v107, v163, v107
	v_pk_mul_f32 v[170:171], v[112:113], v[174:175]
	v_pk_mul_f32 v[174:175], v[114:115], v[176:177]
	v_lshlrev_b64 v[144:145], 8, v[144:145]
	v_pk_mul_f32 v[168:169], v[108:109], v[168:169]
	v_pk_mul_f32 v[166:167], v[110:111], v[166:167]
	v_mul_f32_e32 v161, 0xbfb8aa3b, v161
	v_mul_f32_e32 v163, 0x3fcc422a, v163
	v_cvt_pk_bf16_f32 v170, v170, v171
	v_cvt_pk_bf16_f32 v171, v174, v175
	v_lshl_add_u64 v[144:145], v[172:173], 0, v[144:145]
	v_cvt_pk_bf16_f32 v168, v168, v169
	v_cvt_pk_bf16_f32 v169, v166, v167
	v_exp_f32_e32 v161, v161
	v_mul_f32_e32 v163, 0xbfb8aa3b, v163
	global_store_dwordx2 v[144:145], v[170:171], off sc1
	ds_write_b16 v150, v170 offset:96
	ds_write_b16_d16_hi v150, v170 offset:240
	ds_write_b16 v150, v171 offset:384
	ds_write_b16_d16_hi v150, v171 offset:528
	global_store_dwordx2 v[140:141], v[168:169], off offset:32 sc1
	ds_write_b16 v150, v168 offset:2304
	ds_write_b16_d16_hi v150, v168 offset:2448
	ds_write_b16 v150, v169 offset:2592
	ds_write_b16_d16_hi v150, v169 offset:2736
	global_store_dwordx2 v[138:139], v[164:165], off offset:32 sc1
	ds_write_b16 v150, v164 offset:2336
	ds_write_b16_d16_hi v150, v164 offset:2480
	v_exp_f32_e32 v164, v163
	v_rcp_f32_e32 v163, v135
	v_add_f32_e32 v135, 1.0, v161
	v_rcp_f32_e32 v166, v135
	v_add_f32_e32 v135, 1.0, v164
	v_rcp_f32_e32 v167, v135
	v_mul_f32_e32 v135, 0x3d372713, v96
	v_mul_f32_e32 v135, v96, v135
	v_mul_f32_e32 v161, 0x3d372713, v97
	v_fma_f32 v135, v96, v135, v96
	v_mul_f32_e32 v161, v97, v161
	v_mul_f32_e32 v135, 0x3fcc422a, v135
	v_fma_f32 v161, v97, v161, v97
	v_mul_f32_e32 v135, 0xbfb8aa3b, v135
	v_mul_f32_e32 v161, 0x3fcc422a, v161
	v_exp_f32_e32 v135, v135
	v_mul_f32_e32 v161, 0xbfb8aa3b, v161
	v_exp_f32_e32 v161, v161
	ds_write_b16 v150, v165 offset:2624
	ds_write_b16_d16_hi v150, v165 offset:2768
	v_pk_mul_f32 v[162:163], v[104:105], v[162:163]
	v_pk_mul_f32 v[164:165], v[106:107], v[166:167]
	v_add_f32_e32 v135, 1.0, v135
	v_cvt_pk_bf16_f32 v162, v162, v163
	v_cvt_pk_bf16_f32 v163, v164, v165
	v_rcp_f32_e32 v164, v135
	v_add_f32_e32 v135, 1.0, v161
	v_mul_f32_e32 v161, 0x3d372713, v98
	global_store_dwordx2 v[142:143], v[162:163], off offset:32 sc1
	ds_write_b16 v150, v162 offset:2368
	ds_write_b16_d16_hi v150, v162 offset:2512
	v_mul_f32_e32 v161, v98, v161
	v_mul_f32_e32 v162, 0x3d372713, v99
	v_fma_f32 v161, v98, v161, v98
	v_mul_f32_e32 v162, v99, v162
	v_mul_f32_e32 v161, 0x3fcc422a, v161
	v_fma_f32 v162, v99, v162, v99
	v_mul_f32_e32 v161, 0xbfb8aa3b, v161
	v_mul_f32_e32 v162, 0x3fcc422a, v162
	v_exp_f32_e32 v161, v161
	v_mul_f32_e32 v162, 0xbfb8aa3b, v162
	v_exp_f32_e32 v162, v162
	v_rcp_f32_e32 v165, v135
	v_add_f32_e32 v135, 1.0, v161
	v_rcp_f32_e32 v166, v135
	v_add_f32_e32 v135, 1.0, v162
	v_rcp_f32_e32 v167, v135
	v_fma_f32 v135, v92, v160, v92
	v_mul_f32_e32 v135, 0x3fcc422a, v135
	v_fma_f32 v159, v93, v159, v93
	v_mul_f32_e32 v135, 0xbfb8aa3b, v135
	v_mul_f32_e32 v159, 0x3fcc422a, v159
	v_fma_f32 v158, v94, v158, v94
	v_exp_f32_e32 v135, v135
	v_mul_f32_e32 v159, 0xbfb8aa3b, v159
	v_mul_f32_e32 v158, 0x3fcc422a, v158
	v_fma_f32 v157, v95, v157, v95
	v_exp_f32_e32 v159, v159
	v_mul_f32_e32 v158, 0xbfb8aa3b, v158
	v_mul_f32_e32 v157, 0x3fcc422a, v157
	v_exp_f32_e32 v158, v158
	v_mul_f32_e32 v157, 0xbfb8aa3b, v157
	v_exp_f32_e32 v157, v157
	v_add_f32_e32 v135, 1.0, v135
	v_rcp_f32_e32 v160, v135
	v_add_f32_e32 v135, 1.0, v159
	v_rcp_f32_e32 v161, v135
	v_add_f32_e32 v135, 1.0, v158
	v_rcp_f32_e32 v158, v135
	v_add_f32_e32 v135, 1.0, v157
	v_rcp_f32_e32 v159, v135
	v_mul_f32_e32 v135, v84, v156
	v_fma_f32 v135, v84, v135, v84
	v_mul_f32_e32 v155, v85, v155
	v_mul_f32_e32 v129, v87, v129
	v_mul_f32_e32 v135, 0x3fcc422a, v135
	v_fma_f32 v155, v85, v155, v85
	v_mul_f32_e32 v137, v86, v137
	v_fma_f32 v129, v87, v129, v87
	v_mul_f32_e32 v135, 0xbfb8aa3b, v135
	v_mul_f32_e32 v155, 0x3fcc422a, v155
	v_fma_f32 v137, v86, v137, v86
	v_mul_f32_e32 v129, 0x3fcc422a, v129
	v_exp_f32_e32 v135, v135
	v_mul_f32_e32 v155, 0xbfb8aa3b, v155
	v_mul_f32_e32 v137, 0x3fcc422a, v137
	v_mul_f32_e32 v129, 0xbfb8aa3b, v129
	v_exp_f32_e32 v155, v155
	v_mul_f32_e32 v137, 0xbfb8aa3b, v137
	v_exp_f32_e32 v129, v129
	v_exp_f32_e32 v137, v137
	v_add_f32_e32 v135, 1.0, v135
	v_pk_mul_f32 v[160:161], v[92:93], v[160:161]
	v_pk_mul_f32 v[158:159], v[94:95], v[158:159]
	v_rcp_f32_e32 v156, v135
	v_add_f32_e32 v135, 1.0, v155
	v_add_f32_e32 v129, 1.0, v129
	v_cvt_pk_bf16_f32 v160, v160, v161
	v_cvt_pk_bf16_f32 v161, v158, v159
	v_rcp_f32_e32 v157, v135
	v_add_f32_e32 v135, 1.0, v137
	v_rcp_f32_e32 v159, v129
	v_mul_f32_e32 v129, 0x3d372713, v88
	v_rcp_f32_e32 v158, v135
	v_mul_f32_e32 v129, v88, v129
	v_mul_f32_e32 v135, 0x3d372713, v89
	v_fma_f32 v129, v88, v129, v88
	v_mul_f32_e32 v135, v89, v135
	v_mul_f32_e32 v129, 0x3fcc422a, v129
	v_fma_f32 v135, v89, v135, v89
	v_mul_f32_e32 v129, 0xbfb8aa3b, v129
	v_mul_f32_e32 v135, 0x3fcc422a, v135
	v_exp_f32_e32 v129, v129
	v_mul_f32_e32 v135, 0xbfb8aa3b, v135
	v_exp_f32_e32 v135, v135
	v_pk_mul_f32 v[156:157], v[84:85], v[156:157]
	v_pk_mul_f32 v[158:159], v[86:87], v[158:159]
	v_add_f32_e32 v129, 1.0, v129
	v_cvt_pk_bf16_f32 v156, v156, v157
	v_cvt_pk_bf16_f32 v157, v158, v159
	v_rcp_f32_e32 v158, v129
	v_add_f32_e32 v129, 1.0, v135
	v_mul_f32_e32 v135, 0x3d372713, v90
	v_mul_f32_e32 v135, v90, v135
	v_mul_f32_e32 v137, 0x3d372713, v91
	v_fma_f32 v135, v90, v135, v90
	v_mul_f32_e32 v137, v91, v137
	v_mul_f32_e32 v135, 0x3fcc422a, v135
	v_fma_f32 v137, v91, v137, v91
	v_mul_f32_e32 v135, 0xbfb8aa3b, v135
	v_mul_f32_e32 v137, 0x3fcc422a, v137
	v_exp_f32_e32 v135, v135
	v_mul_f32_e32 v137, 0xbfb8aa3b, v137
	v_exp_f32_e32 v137, v137
	ds_write_b16 v150, v163 offset:2656
	ds_write_b16_d16_hi v150, v163 offset:2800
	v_pk_mul_f32 v[162:163], v[96:97], v[164:165]
	v_pk_mul_f32 v[164:165], v[98:99], v[166:167]
	v_cvt_pk_bf16_f32 v162, v162, v163
	v_cvt_pk_bf16_f32 v163, v164, v165
	v_rcp_f32_e32 v159, v129
	v_add_f32_e32 v129, 1.0, v135
	global_store_dwordx2 v[144:145], v[162:163], off offset:32 sc1
	ds_write_b16 v150, v162 offset:2400
	ds_write_b16_d16_hi v150, v162 offset:2544
	ds_write_b16 v150, v163 offset:2688
	ds_write_b16_d16_hi v150, v163 offset:2832
	global_store_dwordx2 v[140:141], v[160:161], off offset:64 sc1
	ds_write_b16 v150, v160 offset:4608
	ds_write_b16_d16_hi v150, v160 offset:4752
	v_rcp_f32_e32 v160, v129
	v_add_f32_e32 v129, 1.0, v137
	ds_write_b16 v150, v161 offset:4896
	ds_write_b16_d16_hi v150, v161 offset:5040
	v_rcp_f32_e32 v161, v129
	v_mul_f32_e32 v129, 0x3d372713, v80
	v_mul_f32_e32 v129, v80, v129
	v_mul_f32_e32 v135, 0x3d372713, v81
	v_fma_f32 v129, v80, v129, v80
	v_mul_f32_e32 v135, v81, v135
	v_mul_f32_e32 v129, 0x3fcc422a, v129
	v_fma_f32 v135, v81, v135, v81
	v_mul_f32_e32 v129, 0xbfb8aa3b, v129
	v_mul_f32_e32 v135, 0x3fcc422a, v135
	v_exp_f32_e32 v129, v129
	v_mul_f32_e32 v135, 0xbfb8aa3b, v135
	v_exp_f32_e32 v135, v135
	global_store_dwordx2 v[138:139], v[156:157], off offset:64 sc1
	ds_write_b16 v150, v156 offset:4640
	ds_write_b16_d16_hi v150, v156 offset:4784
	ds_write_b16 v150, v157 offset:4928
	ds_write_b16_d16_hi v150, v157 offset:5072
	v_pk_mul_f32 v[156:157], v[88:89], v[158:159]
	v_pk_mul_f32 v[158:159], v[90:91], v[160:161]
	v_add_f32_e32 v129, 1.0, v129
	v_cvt_pk_bf16_f32 v156, v156, v157
	v_cvt_pk_bf16_f32 v157, v158, v159
	v_rcp_f32_e32 v158, v129
	v_add_f32_e32 v129, 1.0, v135
	v_mul_f32_e32 v135, 0x3d372713, v82
	v_mul_f32_e32 v135, v82, v135
	v_mul_f32_e32 v137, 0x3d372713, v83
	v_fma_f32 v135, v82, v135, v82
	v_mul_f32_e32 v137, v83, v137
	v_mul_f32_e32 v135, 0x3fcc422a, v135
	v_fma_f32 v137, v83, v137, v83
	v_mul_f32_e32 v135, 0xbfb8aa3b, v135
	v_mul_f32_e32 v137, 0x3fcc422a, v137
	v_exp_f32_e32 v135, v135
	v_mul_f32_e32 v137, 0xbfb8aa3b, v137
	v_exp_f32_e32 v137, v137
	v_rcp_f32_e32 v159, v129
	v_add_f32_e32 v129, 1.0, v135
	v_rcp_f32_e32 v160, v129
	v_add_f32_e32 v129, 1.0, v137
	v_rcp_f32_e32 v161, v129
	v_mul_f32_e32 v129, 0x3d372713, v76
	v_mul_f32_e32 v129, v76, v129
	v_mul_f32_e32 v135, 0x3d372713, v77
	v_fma_f32 v129, v76, v129, v76
	v_mul_f32_e32 v135, v77, v135
	v_mul_f32_e32 v129, 0x3fcc422a, v129
	v_fma_f32 v135, v77, v135, v77
	v_mul_f32_e32 v129, 0xbfb8aa3b, v129
	v_mul_f32_e32 v135, 0x3fcc422a, v135
	v_exp_f32_e32 v129, v129
	v_mul_f32_e32 v135, 0xbfb8aa3b, v135
	v_exp_f32_e32 v135, v135
	global_store_dwordx2 v[142:143], v[156:157], off offset:64 sc1
	ds_write_b16 v150, v156 offset:4672
	ds_write_b16_d16_hi v150, v156 offset:4816
	ds_write_b16 v150, v157 offset:4960
	ds_write_b16_d16_hi v150, v157 offset:5104
	v_pk_mul_f32 v[156:157], v[80:81], v[158:159]
	v_pk_mul_f32 v[158:159], v[82:83], v[160:161]
	v_add_f32_e32 v129, 1.0, v129
	v_cvt_pk_bf16_f32 v156, v156, v157
	v_cvt_pk_bf16_f32 v157, v158, v159
	v_rcp_f32_e32 v158, v129
	v_add_f32_e32 v129, 1.0, v135
	v_mul_f32_e32 v135, 0x3d372713, v78
	v_mul_f32_e32 v135, v78, v135
	v_mul_f32_e32 v137, 0x3d372713, v79
	v_fma_f32 v135, v78, v135, v78
	v_mul_f32_e32 v137, v79, v137
	v_mul_f32_e32 v135, 0x3fcc422a, v135
	v_fma_f32 v137, v79, v137, v79
	v_mul_f32_e32 v135, 0xbfb8aa3b, v135
	v_mul_f32_e32 v137, 0x3fcc422a, v137
	v_exp_f32_e32 v135, v135
	v_mul_f32_e32 v137, 0xbfb8aa3b, v137
	v_exp_f32_e32 v137, v137
	v_rcp_f32_e32 v159, v129
	v_add_f32_e32 v129, 1.0, v135
	v_rcp_f32_e32 v160, v129
	v_add_f32_e32 v129, 1.0, v137
	v_rcp_f32_e32 v161, v129
	v_mul_f32_e32 v129, 0x3d372713, v68
	v_mul_f32_e32 v129, v68, v129
	v_mul_f32_e32 v135, 0x3d372713, v69
	v_fma_f32 v129, v68, v129, v68
	v_mul_f32_e32 v135, v69, v135
	v_mul_f32_e32 v129, 0x3fcc422a, v129
	v_fma_f32 v135, v69, v135, v69
	v_mul_f32_e32 v129, 0xbfb8aa3b, v129
	v_mul_f32_e32 v135, 0x3fcc422a, v135
	v_exp_f32_e32 v129, v129
	v_mul_f32_e32 v135, 0xbfb8aa3b, v135
	v_exp_f32_e32 v135, v135
	global_store_dwordx2 v[144:145], v[156:157], off offset:64 sc1
	ds_write_b16 v150, v156 offset:4704
	ds_write_b16_d16_hi v150, v156 offset:4848
	ds_write_b16 v150, v157 offset:4992
	ds_write_b16_d16_hi v150, v157 offset:5136
	v_pk_mul_f32 v[156:157], v[76:77], v[158:159]
	v_pk_mul_f32 v[158:159], v[78:79], v[160:161]
	v_add_f32_e32 v129, 1.0, v129
	v_cvt_pk_bf16_f32 v156, v156, v157
	v_cvt_pk_bf16_f32 v157, v158, v159
	v_rcp_f32_e32 v158, v129
	v_add_f32_e32 v129, 1.0, v135
	v_mul_f32_e32 v135, 0x3d372713, v70
	v_mul_f32_e32 v135, v70, v135
	v_mul_f32_e32 v137, 0x3d372713, v71
	v_fma_f32 v135, v70, v135, v70
	v_mul_f32_e32 v137, v71, v137
	v_mul_f32_e32 v135, 0x3fcc422a, v135
	v_fma_f32 v137, v71, v137, v71
	v_mul_f32_e32 v135, 0xbfb8aa3b, v135
	v_mul_f32_e32 v137, 0x3fcc422a, v137
	v_exp_f32_e32 v135, v135
	v_mul_f32_e32 v137, 0xbfb8aa3b, v137
	v_exp_f32_e32 v137, v137
	v_rcp_f32_e32 v159, v129
	v_add_f32_e32 v129, 1.0, v135
	v_rcp_f32_e32 v160, v129
	v_add_f32_e32 v129, 1.0, v137
	v_rcp_f32_e32 v161, v129
	v_mul_f32_e32 v129, 0x3d372713, v72
	v_mul_f32_e32 v129, v72, v129
	v_mul_f32_e32 v135, 0x3d372713, v73
	v_fma_f32 v129, v72, v129, v72
	v_mul_f32_e32 v135, v73, v135
	v_mul_f32_e32 v129, 0x3fcc422a, v129
	v_fma_f32 v135, v73, v135, v73
	v_mul_f32_e32 v129, 0xbfb8aa3b, v129
	v_mul_f32_e32 v135, 0x3fcc422a, v135
	v_exp_f32_e32 v129, v129
	v_mul_f32_e32 v135, 0xbfb8aa3b, v135
	v_exp_f32_e32 v135, v135
	global_store_dwordx2 v[140:141], v[156:157], off offset:96 sc1
	ds_write_b16 v150, v156 offset:6912
	ds_write_b16_d16_hi v150, v156 offset:7056
	ds_write_b16 v150, v157 offset:7200
	ds_write_b16_d16_hi v150, v157 offset:7344
	v_pk_mul_f32 v[156:157], v[68:69], v[158:159]
	v_pk_mul_f32 v[158:159], v[70:71], v[160:161]
	v_add_f32_e32 v129, 1.0, v129
	v_cvt_pk_bf16_f32 v156, v156, v157
	v_cvt_pk_bf16_f32 v157, v158, v159
	v_rcp_f32_e32 v158, v129
	v_add_f32_e32 v129, 1.0, v135
	v_mul_f32_e32 v135, 0x3d372713, v74
	v_mul_f32_e32 v135, v74, v135
	v_mul_f32_e32 v137, 0x3d372713, v75
	v_fma_f32 v135, v74, v135, v74
	v_mul_f32_e32 v137, v75, v137
	v_mul_f32_e32 v135, 0x3fcc422a, v135
	v_fma_f32 v137, v75, v137, v75
	v_mul_f32_e32 v135, 0xbfb8aa3b, v135
	v_mul_f32_e32 v137, 0x3fcc422a, v137
	v_exp_f32_e32 v135, v135
	v_mul_f32_e32 v137, 0xbfb8aa3b, v137
	v_exp_f32_e32 v137, v137
	v_rcp_f32_e32 v159, v129
	v_add_f32_e32 v129, 1.0, v135
	v_rcp_f32_e32 v160, v129
	v_add_f32_e32 v129, 1.0, v137
	v_rcp_f32_e32 v161, v129
	v_mul_f32_e32 v129, 0x3d372713, v64
	v_mul_f32_e32 v129, v64, v129
	v_mul_f32_e32 v135, 0x3d372713, v65
	v_fma_f32 v129, v64, v129, v64
	v_mul_f32_e32 v135, v65, v135
	v_mul_f32_e32 v129, 0x3fcc422a, v129
	v_fma_f32 v135, v65, v135, v65
	v_mul_f32_e32 v129, 0xbfb8aa3b, v129
	v_mul_f32_e32 v135, 0x3fcc422a, v135
	v_exp_f32_e32 v129, v129
	v_mul_f32_e32 v135, 0xbfb8aa3b, v135
	v_exp_f32_e32 v135, v135
	global_store_dwordx2 v[138:139], v[156:157], off offset:96 sc1
	ds_write_b16 v150, v156 offset:6944
	ds_write_b16_d16_hi v150, v156 offset:7088
	ds_write_b16 v150, v157 offset:7232
	ds_write_b16_d16_hi v150, v157 offset:7376
	v_pk_mul_f32 v[156:157], v[72:73], v[158:159]
	v_pk_mul_f32 v[158:159], v[74:75], v[160:161]
	v_add_f32_e32 v129, 1.0, v129
	v_cvt_pk_bf16_f32 v156, v156, v157
	v_cvt_pk_bf16_f32 v157, v158, v159
	v_rcp_f32_e32 v158, v129
	v_add_f32_e32 v129, 1.0, v135
	v_mul_f32_e32 v135, 0x3d372713, v66
	v_mul_f32_e32 v135, v66, v135
	v_mul_f32_e32 v137, 0x3d372713, v67
	v_fma_f32 v135, v66, v135, v66
	v_mul_f32_e32 v137, v67, v137
	v_mul_f32_e32 v135, 0x3fcc422a, v135
	v_fma_f32 v137, v67, v137, v67
	v_mul_f32_e32 v135, 0xbfb8aa3b, v135
	v_mul_f32_e32 v137, 0x3fcc422a, v137
	v_exp_f32_e32 v135, v135
	v_mul_f32_e32 v137, 0xbfb8aa3b, v137
	v_exp_f32_e32 v137, v137
	v_rcp_f32_e32 v159, v129
	v_add_f32_e32 v129, 1.0, v135
	v_rcp_f32_e32 v160, v129
	v_add_f32_e32 v129, 1.0, v137
	v_rcp_f32_e32 v161, v129
	v_mul_f32_e32 v129, 0x3d372713, v60
	v_mul_f32_e32 v129, v60, v129
	v_mul_f32_e32 v135, 0x3d372713, v61
	v_fma_f32 v129, v60, v129, v60
	v_mul_f32_e32 v135, v61, v135
	v_mul_f32_e32 v129, 0x3fcc422a, v129
	v_fma_f32 v135, v61, v135, v61
	v_mul_f32_e32 v129, 0xbfb8aa3b, v129
	v_mul_f32_e32 v135, 0x3fcc422a, v135
	v_exp_f32_e32 v129, v129
	v_mul_f32_e32 v135, 0xbfb8aa3b, v135
	v_exp_f32_e32 v135, v135
	global_store_dwordx2 v[142:143], v[156:157], off offset:96 sc1
	ds_write_b16 v150, v156 offset:6976
	ds_write_b16_d16_hi v150, v156 offset:7120
	ds_write_b16 v150, v157 offset:7264
	ds_write_b16_d16_hi v150, v157 offset:7408
	v_pk_mul_f32 v[156:157], v[64:65], v[158:159]
	v_pk_mul_f32 v[158:159], v[66:67], v[160:161]
	v_add_f32_e32 v129, 1.0, v129
	v_cvt_pk_bf16_f32 v156, v156, v157
	v_cvt_pk_bf16_f32 v157, v158, v159
	v_rcp_f32_e32 v158, v129
	v_add_f32_e32 v129, 1.0, v135
	v_mul_f32_e32 v135, 0x3d372713, v62
	v_mul_f32_e32 v135, v62, v135
	v_mul_f32_e32 v137, 0x3d372713, v63
	v_fma_f32 v135, v62, v135, v62
	v_mul_f32_e32 v137, v63, v137
	v_mul_f32_e32 v135, 0x3fcc422a, v135
	v_fma_f32 v137, v63, v137, v63
	v_mul_f32_e32 v135, 0xbfb8aa3b, v135
	v_mul_f32_e32 v137, 0x3fcc422a, v137
	v_exp_f32_e32 v135, v135
	v_mul_f32_e32 v137, 0xbfb8aa3b, v137
	v_exp_f32_e32 v137, v137
	v_rcp_f32_e32 v159, v129
	v_add_f32_e32 v129, 1.0, v135
	v_rcp_f32_e32 v160, v129
	v_add_f32_e32 v129, 1.0, v137
	v_rcp_f32_e32 v161, v129
	v_mul_f32_e32 v129, 0x3d372713, v52
	v_mul_f32_e32 v129, v52, v129
	v_mul_f32_e32 v135, 0x3d372713, v53
	v_fma_f32 v129, v52, v129, v52
	v_mul_f32_e32 v135, v53, v135
	v_mul_f32_e32 v129, 0x3fcc422a, v129
	v_fma_f32 v135, v53, v135, v53
	v_mul_f32_e32 v129, 0xbfb8aa3b, v129
	v_mul_f32_e32 v135, 0x3fcc422a, v135
	v_exp_f32_e32 v129, v129
	v_mul_f32_e32 v135, 0xbfb8aa3b, v135
	v_exp_f32_e32 v135, v135
	global_store_dwordx2 v[144:145], v[156:157], off offset:96 sc1
	ds_write_b16 v150, v156 offset:7008
	ds_write_b16_d16_hi v150, v156 offset:7152
	ds_write_b16 v150, v157 offset:7296
	ds_write_b16_d16_hi v150, v157 offset:7440
	v_pk_mul_f32 v[156:157], v[60:61], v[158:159]
	v_pk_mul_f32 v[158:159], v[62:63], v[160:161]
	v_add_f32_e32 v129, 1.0, v129
	v_cvt_pk_bf16_f32 v156, v156, v157
	v_cvt_pk_bf16_f32 v157, v158, v159
	v_rcp_f32_e32 v158, v129
	v_add_f32_e32 v129, 1.0, v135
	v_mul_f32_e32 v135, 0x3d372713, v54
	v_mul_f32_e32 v135, v54, v135
	v_mul_f32_e32 v137, 0x3d372713, v55
	v_fma_f32 v135, v54, v135, v54
	v_mul_f32_e32 v137, v55, v137
	v_mul_f32_e32 v135, 0x3fcc422a, v135
	v_fma_f32 v137, v55, v137, v55
	v_mul_f32_e32 v135, 0xbfb8aa3b, v135
	v_mul_f32_e32 v137, 0x3fcc422a, v137
	v_exp_f32_e32 v135, v135
	v_mul_f32_e32 v137, 0xbfb8aa3b, v137
	v_exp_f32_e32 v137, v137
	v_rcp_f32_e32 v159, v129
	v_add_f32_e32 v129, 1.0, v135
	v_rcp_f32_e32 v160, v129
	v_add_f32_e32 v129, 1.0, v137
	v_rcp_f32_e32 v161, v129
	v_mul_f32_e32 v129, 0x3d372713, v56
	v_mul_f32_e32 v129, v56, v129
	v_mul_f32_e32 v135, 0x3d372713, v57
	v_fma_f32 v129, v56, v129, v56
	v_mul_f32_e32 v135, v57, v135
	v_mul_f32_e32 v129, 0x3fcc422a, v129
	v_fma_f32 v135, v57, v135, v57
	v_mul_f32_e32 v129, 0xbfb8aa3b, v129
	v_mul_f32_e32 v135, 0x3fcc422a, v135
	v_exp_f32_e32 v129, v129
	v_mul_f32_e32 v135, 0xbfb8aa3b, v135
	v_exp_f32_e32 v135, v135
	global_store_dwordx2 v[140:141], v[156:157], off offset:128 sc1
	ds_write_b16 v150, v156 offset:9216
	ds_write_b16_d16_hi v150, v156 offset:9360
	ds_write_b16 v150, v157 offset:9504
	ds_write_b16_d16_hi v150, v157 offset:9648
	v_pk_mul_f32 v[156:157], v[52:53], v[158:159]
	v_pk_mul_f32 v[158:159], v[54:55], v[160:161]
	v_add_f32_e32 v129, 1.0, v129
	v_cvt_pk_bf16_f32 v156, v156, v157
	v_cvt_pk_bf16_f32 v157, v158, v159
	v_rcp_f32_e32 v158, v129
	v_add_f32_e32 v129, 1.0, v135
	v_mul_f32_e32 v135, 0x3d372713, v58
	v_mul_f32_e32 v135, v58, v135
	v_mul_f32_e32 v137, 0x3d372713, v59
	v_fma_f32 v135, v58, v135, v58
	v_mul_f32_e32 v137, v59, v137
	v_mul_f32_e32 v135, 0x3fcc422a, v135
	v_fma_f32 v137, v59, v137, v59
	v_mul_f32_e32 v135, 0xbfb8aa3b, v135
	v_mul_f32_e32 v137, 0x3fcc422a, v137
	v_exp_f32_e32 v135, v135
	v_mul_f32_e32 v137, 0xbfb8aa3b, v137
	v_exp_f32_e32 v137, v137
	v_rcp_f32_e32 v159, v129
	v_add_f32_e32 v129, 1.0, v135
	v_rcp_f32_e32 v160, v129
	v_add_f32_e32 v129, 1.0, v137
	v_rcp_f32_e32 v161, v129
	v_mul_f32_e32 v129, 0x3d372713, v48
	v_mul_f32_e32 v129, v48, v129
	v_mul_f32_e32 v135, 0x3d372713, v49
	v_fma_f32 v129, v48, v129, v48
	v_mul_f32_e32 v135, v49, v135
	v_mul_f32_e32 v129, 0x3fcc422a, v129
	v_fma_f32 v135, v49, v135, v49
	v_mul_f32_e32 v129, 0xbfb8aa3b, v129
	v_mul_f32_e32 v135, 0x3fcc422a, v135
	v_exp_f32_e32 v129, v129
	v_mul_f32_e32 v135, 0xbfb8aa3b, v135
	v_exp_f32_e32 v135, v135
	global_store_dwordx2 v[138:139], v[156:157], off offset:128 sc1
	ds_write_b16 v150, v156 offset:9248
	ds_write_b16_d16_hi v150, v156 offset:9392
	ds_write_b16 v150, v157 offset:9536
	ds_write_b16_d16_hi v150, v157 offset:9680
	v_pk_mul_f32 v[156:157], v[56:57], v[158:159]
	v_pk_mul_f32 v[158:159], v[58:59], v[160:161]
	v_add_f32_e32 v129, 1.0, v129
	v_cvt_pk_bf16_f32 v156, v156, v157
	v_cvt_pk_bf16_f32 v157, v158, v159
	v_rcp_f32_e32 v158, v129
	v_add_f32_e32 v129, 1.0, v135
	v_mul_f32_e32 v135, 0x3d372713, v50
	v_mul_f32_e32 v135, v50, v135
	v_mul_f32_e32 v137, 0x3d372713, v51
	v_fma_f32 v135, v50, v135, v50
	v_mul_f32_e32 v137, v51, v137
	v_mul_f32_e32 v135, 0x3fcc422a, v135
	v_fma_f32 v137, v51, v137, v51
	v_mul_f32_e32 v135, 0xbfb8aa3b, v135
	v_mul_f32_e32 v137, 0x3fcc422a, v137
	v_exp_f32_e32 v135, v135
	v_mul_f32_e32 v137, 0xbfb8aa3b, v137
	v_exp_f32_e32 v137, v137
	v_rcp_f32_e32 v159, v129
	v_add_f32_e32 v129, 1.0, v135
	v_rcp_f32_e32 v160, v129
	v_add_f32_e32 v129, 1.0, v137
	v_rcp_f32_e32 v161, v129
	v_mul_f32_e32 v129, 0x3d372713, v44
	v_mul_f32_e32 v129, v44, v129
	v_mul_f32_e32 v135, 0x3d372713, v45
	v_fma_f32 v129, v44, v129, v44
	v_mul_f32_e32 v135, v45, v135
	v_mul_f32_e32 v129, 0x3fcc422a, v129
	v_fma_f32 v135, v45, v135, v45
	v_mul_f32_e32 v129, 0xbfb8aa3b, v129
	v_mul_f32_e32 v135, 0x3fcc422a, v135
	v_exp_f32_e32 v129, v129
	v_mul_f32_e32 v135, 0xbfb8aa3b, v135
	v_exp_f32_e32 v135, v135
	global_store_dwordx2 v[142:143], v[156:157], off offset:128 sc1
	ds_write_b16 v150, v156 offset:9280
	ds_write_b16_d16_hi v150, v156 offset:9424
	ds_write_b16 v150, v157 offset:9568
	ds_write_b16_d16_hi v150, v157 offset:9712
	v_pk_mul_f32 v[156:157], v[48:49], v[158:159]
	v_pk_mul_f32 v[158:159], v[50:51], v[160:161]
	v_add_f32_e32 v129, 1.0, v129
	v_cvt_pk_bf16_f32 v156, v156, v157
	v_cvt_pk_bf16_f32 v157, v158, v159
	v_rcp_f32_e32 v158, v129
	v_add_f32_e32 v129, 1.0, v135
	v_mul_f32_e32 v135, 0x3d372713, v46
	v_mul_f32_e32 v135, v46, v135
	v_mul_f32_e32 v137, 0x3d372713, v47
	v_fma_f32 v135, v46, v135, v46
	v_mul_f32_e32 v137, v47, v137
	v_mul_f32_e32 v135, 0x3fcc422a, v135
	v_fma_f32 v137, v47, v137, v47
	v_mul_f32_e32 v135, 0xbfb8aa3b, v135
	v_mul_f32_e32 v137, 0x3fcc422a, v137
	v_exp_f32_e32 v135, v135
	v_mul_f32_e32 v137, 0xbfb8aa3b, v137
	v_exp_f32_e32 v137, v137
	v_rcp_f32_e32 v159, v129
	v_add_f32_e32 v129, 1.0, v135
	v_rcp_f32_e32 v160, v129
	v_add_f32_e32 v129, 1.0, v137
	v_rcp_f32_e32 v161, v129
	v_mul_f32_e32 v129, 0x3d372713, v36
	v_mul_f32_e32 v129, v36, v129
	v_mul_f32_e32 v135, 0x3d372713, v37
	v_fma_f32 v129, v36, v129, v36
	v_mul_f32_e32 v135, v37, v135
	v_mul_f32_e32 v129, 0x3fcc422a, v129
	v_fma_f32 v135, v37, v135, v37
	v_mul_f32_e32 v129, 0xbfb8aa3b, v129
	v_mul_f32_e32 v135, 0x3fcc422a, v135
	v_exp_f32_e32 v129, v129
	v_mul_f32_e32 v135, 0xbfb8aa3b, v135
	v_exp_f32_e32 v135, v135
	global_store_dwordx2 v[144:145], v[156:157], off offset:128 sc1
	ds_write_b16 v150, v156 offset:9312
	ds_write_b16_d16_hi v150, v156 offset:9456
	ds_write_b16 v150, v157 offset:9600
	ds_write_b16_d16_hi v150, v157 offset:9744
	v_pk_mul_f32 v[156:157], v[44:45], v[158:159]
	v_pk_mul_f32 v[158:159], v[46:47], v[160:161]
	v_add_f32_e32 v129, 1.0, v129
	v_cvt_pk_bf16_f32 v156, v156, v157
	v_cvt_pk_bf16_f32 v157, v158, v159
	v_rcp_f32_e32 v158, v129
	v_add_f32_e32 v129, 1.0, v135
	v_mul_f32_e32 v135, 0x3d372713, v38
	v_mul_f32_e32 v135, v38, v135
	v_mul_f32_e32 v137, 0x3d372713, v39
	v_fma_f32 v135, v38, v135, v38
	v_mul_f32_e32 v137, v39, v137
	v_mul_f32_e32 v135, 0x3fcc422a, v135
	v_fma_f32 v137, v39, v137, v39
	v_mul_f32_e32 v135, 0xbfb8aa3b, v135
	v_mul_f32_e32 v137, 0x3fcc422a, v137
	v_exp_f32_e32 v135, v135
	v_mul_f32_e32 v137, 0xbfb8aa3b, v137
	v_exp_f32_e32 v137, v137
	v_rcp_f32_e32 v159, v129
	v_add_f32_e32 v129, 1.0, v135
	v_rcp_f32_e32 v160, v129
	v_add_f32_e32 v129, 1.0, v137
	v_rcp_f32_e32 v161, v129
	v_mul_f32_e32 v129, 0x3d372713, v40
	v_mul_f32_e32 v129, v40, v129
	v_mul_f32_e32 v135, 0x3d372713, v41
	v_fma_f32 v129, v40, v129, v40
	v_mul_f32_e32 v135, v41, v135
	v_mul_f32_e32 v129, 0x3fcc422a, v129
	v_fma_f32 v135, v41, v135, v41
	v_mul_f32_e32 v129, 0xbfb8aa3b, v129
	v_mul_f32_e32 v135, 0x3fcc422a, v135
	v_exp_f32_e32 v129, v129
	v_mul_f32_e32 v135, 0xbfb8aa3b, v135
	v_exp_f32_e32 v135, v135
	global_store_dwordx2 v[140:141], v[156:157], off offset:160 sc1
	ds_write_b16 v150, v156 offset:11520
	ds_write_b16_d16_hi v150, v156 offset:11664
	ds_write_b16 v150, v157 offset:11808
	ds_write_b16_d16_hi v150, v157 offset:11952
	v_pk_mul_f32 v[156:157], v[36:37], v[158:159]
	v_pk_mul_f32 v[158:159], v[38:39], v[160:161]
	v_add_f32_e32 v129, 1.0, v129
	v_cvt_pk_bf16_f32 v156, v156, v157
	v_cvt_pk_bf16_f32 v157, v158, v159
	v_rcp_f32_e32 v158, v129
	v_add_f32_e32 v129, 1.0, v135
	v_mul_f32_e32 v135, 0x3d372713, v42
	v_mul_f32_e32 v135, v42, v135
	v_mul_f32_e32 v137, 0x3d372713, v43
	v_fma_f32 v135, v42, v135, v42
	v_mul_f32_e32 v137, v43, v137
	v_mul_f32_e32 v135, 0x3fcc422a, v135
	v_fma_f32 v137, v43, v137, v43
	v_mul_f32_e32 v135, 0xbfb8aa3b, v135
	v_mul_f32_e32 v137, 0x3fcc422a, v137
	v_exp_f32_e32 v135, v135
	v_mul_f32_e32 v137, 0xbfb8aa3b, v137
	v_exp_f32_e32 v137, v137
	v_rcp_f32_e32 v159, v129
	v_add_f32_e32 v129, 1.0, v135
	v_rcp_f32_e32 v160, v129
	v_add_f32_e32 v129, 1.0, v137
	v_rcp_f32_e32 v161, v129
	v_mul_f32_e32 v129, 0x3d372713, v32
	v_mul_f32_e32 v129, v32, v129
	v_mul_f32_e32 v135, 0x3d372713, v33
	v_fma_f32 v129, v32, v129, v32
	v_mul_f32_e32 v135, v33, v135
	v_mul_f32_e32 v129, 0x3fcc422a, v129
	v_fma_f32 v135, v33, v135, v33
	v_mul_f32_e32 v129, 0xbfb8aa3b, v129
	v_mul_f32_e32 v135, 0x3fcc422a, v135
	v_exp_f32_e32 v129, v129
	v_mul_f32_e32 v135, 0xbfb8aa3b, v135
	v_exp_f32_e32 v135, v135
	global_store_dwordx2 v[138:139], v[156:157], off offset:160 sc1
	ds_write_b16 v150, v156 offset:11552
	ds_write_b16_d16_hi v150, v156 offset:11696
	ds_write_b16 v150, v157 offset:11840
	ds_write_b16_d16_hi v150, v157 offset:11984
	v_pk_mul_f32 v[156:157], v[40:41], v[158:159]
	v_pk_mul_f32 v[158:159], v[42:43], v[160:161]
	v_add_f32_e32 v129, 1.0, v129
	v_cvt_pk_bf16_f32 v156, v156, v157
	v_cvt_pk_bf16_f32 v157, v158, v159
	v_rcp_f32_e32 v158, v129
	v_add_f32_e32 v129, 1.0, v135
	v_mul_f32_e32 v135, 0x3d372713, v34
	v_mul_f32_e32 v135, v34, v135
	v_mul_f32_e32 v137, 0x3d372713, v35
	v_fma_f32 v135, v34, v135, v34
	v_mul_f32_e32 v137, v35, v137
	v_mul_f32_e32 v135, 0x3fcc422a, v135
	v_fma_f32 v137, v35, v137, v35
	v_mul_f32_e32 v135, 0xbfb8aa3b, v135
	v_mul_f32_e32 v137, 0x3fcc422a, v137
	v_exp_f32_e32 v135, v135
	v_mul_f32_e32 v137, 0xbfb8aa3b, v137
	v_exp_f32_e32 v137, v137
	v_rcp_f32_e32 v159, v129
	v_add_f32_e32 v129, 1.0, v135
	v_rcp_f32_e32 v160, v129
	v_add_f32_e32 v129, 1.0, v137
	v_rcp_f32_e32 v161, v129
	v_mul_f32_e32 v129, 0x3d372713, v28
	v_mul_f32_e32 v129, v28, v129
	v_mul_f32_e32 v135, 0x3d372713, v29
	v_fma_f32 v129, v28, v129, v28
	v_mul_f32_e32 v135, v29, v135
	v_mul_f32_e32 v129, 0x3fcc422a, v129
	v_fma_f32 v135, v29, v135, v29
	v_mul_f32_e32 v129, 0xbfb8aa3b, v129
	v_mul_f32_e32 v135, 0x3fcc422a, v135
	v_exp_f32_e32 v129, v129
	v_mul_f32_e32 v135, 0xbfb8aa3b, v135
	v_exp_f32_e32 v135, v135
	global_store_dwordx2 v[142:143], v[156:157], off offset:160 sc1
	ds_write_b16 v150, v156 offset:11584
	ds_write_b16_d16_hi v150, v156 offset:11728
	ds_write_b16 v150, v157 offset:11872
	ds_write_b16_d16_hi v150, v157 offset:12016
	v_pk_mul_f32 v[156:157], v[32:33], v[158:159]
	v_pk_mul_f32 v[158:159], v[34:35], v[160:161]
	v_add_f32_e32 v129, 1.0, v129
	v_cvt_pk_bf16_f32 v156, v156, v157
	v_cvt_pk_bf16_f32 v157, v158, v159
	v_rcp_f32_e32 v158, v129
	v_add_f32_e32 v129, 1.0, v135
	v_mul_f32_e32 v135, 0x3d372713, v30
	v_mul_f32_e32 v135, v30, v135
	v_mul_f32_e32 v137, 0x3d372713, v31
	v_fma_f32 v135, v30, v135, v30
	v_mul_f32_e32 v137, v31, v137
	v_mul_f32_e32 v135, 0x3fcc422a, v135
	v_fma_f32 v137, v31, v137, v31
	v_mul_f32_e32 v135, 0xbfb8aa3b, v135
	v_mul_f32_e32 v137, 0x3fcc422a, v137
	v_exp_f32_e32 v135, v135
	v_mul_f32_e32 v137, 0xbfb8aa3b, v137
	v_exp_f32_e32 v137, v137
	v_rcp_f32_e32 v159, v129
	v_add_f32_e32 v129, 1.0, v135
	v_rcp_f32_e32 v160, v129
	v_add_f32_e32 v129, 1.0, v137
	v_rcp_f32_e32 v161, v129
	v_mul_f32_e32 v129, 0x3d372713, v16
	v_mul_f32_e32 v129, v16, v129
	v_mul_f32_e32 v135, 0x3d372713, v17
	v_fma_f32 v129, v16, v129, v16
	v_mul_f32_e32 v135, v17, v135
	v_mul_f32_e32 v129, 0x3fcc422a, v129
	v_fma_f32 v135, v17, v135, v17
	v_mul_f32_e32 v129, 0xbfb8aa3b, v129
	v_mul_f32_e32 v135, 0x3fcc422a, v135
	v_exp_f32_e32 v129, v129
	v_mul_f32_e32 v135, 0xbfb8aa3b, v135
	v_exp_f32_e32 v135, v135
	global_store_dwordx2 v[144:145], v[156:157], off offset:160 sc1
	ds_write_b16 v150, v156 offset:11616
	ds_write_b16_d16_hi v150, v156 offset:11760
	ds_write_b16 v150, v157 offset:11904
	ds_write_b16_d16_hi v150, v157 offset:12048
	v_pk_mul_f32 v[156:157], v[28:29], v[158:159]
	v_pk_mul_f32 v[158:159], v[30:31], v[160:161]
	v_add_f32_e32 v129, 1.0, v129
	v_cvt_pk_bf16_f32 v156, v156, v157
	v_cvt_pk_bf16_f32 v157, v158, v159
	v_rcp_f32_e32 v158, v129
	v_add_f32_e32 v129, 1.0, v135
	v_mul_f32_e32 v135, 0x3d372713, v18
	v_mul_f32_e32 v135, v18, v135
	v_mul_f32_e32 v137, 0x3d372713, v19
	v_fma_f32 v135, v18, v135, v18
	v_mul_f32_e32 v137, v19, v137
	v_mul_f32_e32 v135, 0x3fcc422a, v135
	v_fma_f32 v137, v19, v137, v19
	v_mul_f32_e32 v135, 0xbfb8aa3b, v135
	v_mul_f32_e32 v137, 0x3fcc422a, v137
	v_exp_f32_e32 v135, v135
	v_mul_f32_e32 v137, 0xbfb8aa3b, v137
	v_exp_f32_e32 v137, v137
	v_rcp_f32_e32 v159, v129
	v_add_f32_e32 v129, 1.0, v135
	v_rcp_f32_e32 v160, v129
	v_add_f32_e32 v129, 1.0, v137
	v_rcp_f32_e32 v161, v129
	v_mul_f32_e32 v129, 0x3d372713, v24
	v_mul_f32_e32 v129, v24, v129
	v_mul_f32_e32 v135, 0x3d372713, v25
	v_fma_f32 v129, v24, v129, v24
	v_mul_f32_e32 v135, v25, v135
	v_mul_f32_e32 v129, 0x3fcc422a, v129
	v_fma_f32 v135, v25, v135, v25
	v_mul_f32_e32 v129, 0xbfb8aa3b, v129
	v_mul_f32_e32 v135, 0x3fcc422a, v135
	v_exp_f32_e32 v129, v129
	v_mul_f32_e32 v135, 0xbfb8aa3b, v135
	v_exp_f32_e32 v135, v135
	global_store_dwordx2 v[140:141], v[156:157], off offset:192 sc1
	ds_write_b16 v150, v156 offset:13824
	ds_write_b16_d16_hi v150, v156 offset:13968
	ds_write_b16 v150, v157 offset:14112
	ds_write_b16_d16_hi v150, v157 offset:14256
	v_pk_mul_f32 v[156:157], v[16:17], v[158:159]
	v_pk_mul_f32 v[158:159], v[18:19], v[160:161]
	v_add_f32_e32 v129, 1.0, v129
	v_cvt_pk_bf16_f32 v156, v156, v157
	v_cvt_pk_bf16_f32 v157, v158, v159
	v_rcp_f32_e32 v158, v129
	v_add_f32_e32 v129, 1.0, v135
	v_mul_f32_e32 v135, 0x3d372713, v26
	v_mul_f32_e32 v135, v26, v135
	v_mul_f32_e32 v137, 0x3d372713, v27
	v_fma_f32 v135, v26, v135, v26
	v_mul_f32_e32 v137, v27, v137
	v_mul_f32_e32 v135, 0x3fcc422a, v135
	v_fma_f32 v137, v27, v137, v27
	v_mul_f32_e32 v135, 0xbfb8aa3b, v135
	v_mul_f32_e32 v137, 0x3fcc422a, v137
	v_exp_f32_e32 v135, v135
	v_mul_f32_e32 v137, 0xbfb8aa3b, v137
	v_exp_f32_e32 v137, v137
	v_rcp_f32_e32 v159, v129
	v_add_f32_e32 v129, 1.0, v135
	v_rcp_f32_e32 v160, v129
	v_add_f32_e32 v129, 1.0, v137
	v_rcp_f32_e32 v161, v129
	v_mul_f32_e32 v129, 0x3d372713, v12
	v_mul_f32_e32 v129, v12, v129
	v_mul_f32_e32 v135, 0x3d372713, v13
	v_fma_f32 v129, v12, v129, v12
	v_mul_f32_e32 v135, v13, v135
	v_mul_f32_e32 v129, 0x3fcc422a, v129
	v_fma_f32 v135, v13, v135, v13
	v_mul_f32_e32 v129, 0xbfb8aa3b, v129
	v_mul_f32_e32 v135, 0x3fcc422a, v135
	v_exp_f32_e32 v129, v129
	v_mul_f32_e32 v135, 0xbfb8aa3b, v135
	v_exp_f32_e32 v135, v135
	global_store_dwordx2 v[138:139], v[156:157], off offset:192 sc1
	ds_write_b16 v150, v156 offset:13856
	ds_write_b16_d16_hi v150, v156 offset:14000
	ds_write_b16 v150, v157 offset:14144
	ds_write_b16_d16_hi v150, v157 offset:14288
	v_pk_mul_f32 v[156:157], v[24:25], v[158:159]
	v_pk_mul_f32 v[158:159], v[26:27], v[160:161]
	v_add_f32_e32 v129, 1.0, v129
	v_cvt_pk_bf16_f32 v156, v156, v157
	v_cvt_pk_bf16_f32 v157, v158, v159
	v_rcp_f32_e32 v158, v129
	v_add_f32_e32 v129, 1.0, v135
	v_mul_f32_e32 v135, 0x3d372713, v14
	v_mul_f32_e32 v135, v14, v135
	v_mul_f32_e32 v137, 0x3d372713, v15
	v_fma_f32 v135, v14, v135, v14
	v_mul_f32_e32 v137, v15, v137
	v_mul_f32_e32 v135, 0x3fcc422a, v135
	v_fma_f32 v137, v15, v137, v15
	v_mul_f32_e32 v135, 0xbfb8aa3b, v135
	v_mul_f32_e32 v137, 0x3fcc422a, v137
	v_exp_f32_e32 v135, v135
	v_mul_f32_e32 v137, 0xbfb8aa3b, v137
	v_exp_f32_e32 v137, v137
	v_rcp_f32_e32 v159, v129
	v_add_f32_e32 v129, 1.0, v135
	v_rcp_f32_e32 v160, v129
	v_add_f32_e32 v129, 1.0, v137
	v_rcp_f32_e32 v161, v129
	v_mul_f32_e32 v129, 0x3d372713, v4
	v_mul_f32_e32 v129, v4, v129
	v_mul_f32_e32 v135, 0x3d372713, v5
	v_fma_f32 v129, v4, v129, v4
	v_mul_f32_e32 v135, v5, v135
	v_mul_f32_e32 v129, 0x3fcc422a, v129
	v_fma_f32 v135, v5, v135, v5
	v_mul_f32_e32 v129, 0xbfb8aa3b, v129
	v_mul_f32_e32 v135, 0x3fcc422a, v135
	v_exp_f32_e32 v129, v129
	v_mul_f32_e32 v135, 0xbfb8aa3b, v135
	v_exp_f32_e32 v135, v135
	global_store_dwordx2 v[142:143], v[156:157], off offset:192 sc1
	ds_write_b16 v150, v156 offset:13888
	ds_write_b16_d16_hi v150, v156 offset:14032
	ds_write_b16 v150, v157 offset:14176
	ds_write_b16_d16_hi v150, v157 offset:14320
	v_pk_mul_f32 v[156:157], v[12:13], v[158:159]
	v_pk_mul_f32 v[158:159], v[14:15], v[160:161]
	v_add_f32_e32 v129, 1.0, v129
	v_cvt_pk_bf16_f32 v156, v156, v157
	v_cvt_pk_bf16_f32 v157, v158, v159
	v_rcp_f32_e32 v158, v129
	v_add_f32_e32 v129, 1.0, v135
	v_mul_f32_e32 v135, 0x3d372713, v6
	v_mul_f32_e32 v135, v6, v135
	v_mul_f32_e32 v137, 0x3d372713, v7
	v_fma_f32 v135, v6, v135, v6
	v_mul_f32_e32 v137, v7, v137
	v_mul_f32_e32 v135, 0x3fcc422a, v135
	v_fma_f32 v137, v7, v137, v7
	v_mul_f32_e32 v135, 0xbfb8aa3b, v135
	v_mul_f32_e32 v137, 0x3fcc422a, v137
	v_exp_f32_e32 v135, v135
	v_mul_f32_e32 v137, 0xbfb8aa3b, v137
	v_exp_f32_e32 v137, v137
	v_rcp_f32_e32 v159, v129
	v_add_f32_e32 v129, 1.0, v135
	v_rcp_f32_e32 v160, v129
	v_add_f32_e32 v129, 1.0, v137
	v_rcp_f32_e32 v161, v129
	v_mul_f32_e32 v129, 0x3d372713, v0
	v_mul_f32_e32 v129, v0, v129
	v_mul_f32_e32 v135, 0x3d372713, v1
	v_fma_f32 v129, v0, v129, v0
	v_mul_f32_e32 v135, v1, v135
	v_mul_f32_e32 v129, 0x3fcc422a, v129
	v_fma_f32 v135, v1, v135, v1
	v_mul_f32_e32 v129, 0xbfb8aa3b, v129
	v_mul_f32_e32 v135, 0x3fcc422a, v135
	v_exp_f32_e32 v129, v129
	v_mul_f32_e32 v135, 0xbfb8aa3b, v135
	v_exp_f32_e32 v135, v135
	global_store_dwordx2 v[144:145], v[156:157], off offset:192 sc1
	ds_write_b16 v150, v156 offset:13920
	ds_write_b16_d16_hi v150, v156 offset:14064
	ds_write_b16 v150, v157 offset:14208
	ds_write_b16_d16_hi v150, v157 offset:14352
	v_pk_mul_f32 v[156:157], v[4:5], v[158:159]
	v_pk_mul_f32 v[158:159], v[6:7], v[160:161]
	v_cvt_pk_bf16_f32 v156, v156, v157
	v_cvt_pk_bf16_f32 v157, v158, v159
	v_add_f32_e32 v129, 1.0, v129
	global_store_dwordx2 v[140:141], v[156:157], off offset:224 sc1
	v_rcp_f32_e32 v140, v129
	v_add_f32_e32 v129, 1.0, v135
	v_mul_f32_e32 v135, 0x3d372713, v2
	v_mul_f32_e32 v135, v2, v135
	v_mul_f32_e32 v137, 0x3d372713, v3
	v_fma_f32 v135, v2, v135, v2
	v_mul_f32_e32 v137, v3, v137
	v_mul_f32_e32 v135, 0x3fcc422a, v135
	v_fma_f32 v137, v3, v137, v3
	v_mul_f32_e32 v135, 0xbfb8aa3b, v135
	v_mul_f32_e32 v137, 0x3fcc422a, v137
	v_exp_f32_e32 v135, v135
	v_mul_f32_e32 v137, 0xbfb8aa3b, v137
	v_exp_f32_e32 v137, v137
	v_rcp_f32_e32 v141, v129
	v_add_f32_e32 v129, 1.0, v135
	v_rcp_f32_e32 v158, v129
	v_add_f32_e32 v129, 1.0, v137
	v_rcp_f32_e32 v159, v129
	v_mul_f32_e32 v129, 0x3d372713, v20
	v_mul_f32_e32 v129, v20, v129
	v_mul_f32_e32 v135, 0x3d372713, v21
	v_fma_f32 v129, v20, v129, v20
	v_mul_f32_e32 v135, v21, v135
	v_mul_f32_e32 v129, 0x3fcc422a, v129
	v_fma_f32 v135, v21, v135, v21
	v_mul_f32_e32 v129, 0xbfb8aa3b, v129
	v_mul_f32_e32 v135, 0x3fcc422a, v135
	v_exp_f32_e32 v129, v129
	v_mul_f32_e32 v135, 0xbfb8aa3b, v135
	v_exp_f32_e32 v135, v135
	ds_write_b16 v150, v156 offset:16128
	ds_write_b16_d16_hi v150, v156 offset:16272
	ds_write_b16 v150, v157 offset:16416
	ds_write_b16_d16_hi v150, v157 offset:16560
	v_pk_mul_f32 v[140:141], v[0:1], v[140:141]
	v_pk_mul_f32 v[156:157], v[2:3], v[158:159]
	v_cvt_pk_bf16_f32 v140, v140, v141
	v_cvt_pk_bf16_f32 v141, v156, v157
	v_add_f32_e32 v129, 1.0, v129
	global_store_dwordx2 v[138:139], v[140:141], off offset:224 sc1
	v_rcp_f32_e32 v138, v129
	v_add_f32_e32 v129, 1.0, v135
	v_mul_f32_e32 v135, 0x3d372713, v22
	v_mul_f32_e32 v135, v22, v135
	v_mul_f32_e32 v137, 0x3d372713, v23
	v_fma_f32 v135, v22, v135, v22
	v_mul_f32_e32 v137, v23, v137
	v_mul_f32_e32 v135, 0x3fcc422a, v135
	v_fma_f32 v137, v23, v137, v23
	v_mul_f32_e32 v135, 0xbfb8aa3b, v135
	v_mul_f32_e32 v137, 0x3fcc422a, v137
	v_exp_f32_e32 v135, v135
	v_mul_f32_e32 v137, 0xbfb8aa3b, v137
	v_exp_f32_e32 v137, v137
	v_rcp_f32_e32 v139, v129
	v_add_f32_e32 v129, 1.0, v135
	v_rcp_f32_e32 v156, v129
	v_add_f32_e32 v129, 1.0, v137
	v_rcp_f32_e32 v157, v129
	v_mul_f32_e32 v129, 0x3d372713, v8
	v_mul_f32_e32 v129, v8, v129
	v_mul_f32_e32 v135, 0x3d372713, v9
	v_fma_f32 v129, v8, v129, v8
	v_mul_f32_e32 v135, v9, v135
	v_mul_f32_e32 v129, 0x3fcc422a, v129
	v_fma_f32 v135, v9, v135, v9
	v_mul_f32_e32 v129, 0xbfb8aa3b, v129
	v_mul_f32_e32 v135, 0x3fcc422a, v135
	v_exp_f32_e32 v129, v129
	v_mul_f32_e32 v135, 0xbfb8aa3b, v135
	v_exp_f32_e32 v135, v135
	ds_write_b16 v150, v140 offset:16160
	ds_write_b16_d16_hi v150, v140 offset:16304
	ds_write_b16 v150, v141 offset:16448
	ds_write_b16_d16_hi v150, v141 offset:16592
	v_pk_mul_f32 v[138:139], v[20:21], v[138:139]
	v_pk_mul_f32 v[140:141], v[22:23], v[156:157]
	v_add_f32_e32 v129, 1.0, v129
	v_cvt_pk_bf16_f32 v138, v138, v139
	v_cvt_pk_bf16_f32 v139, v140, v141
	v_rcp_f32_e32 v140, v129
	v_add_f32_e32 v129, 1.0, v135
	v_mul_f32_e32 v135, 0x3d372713, v10
	v_mul_f32_e32 v135, v10, v135
	v_mul_f32_e32 v137, 0x3d372713, v11
	v_fma_f32 v135, v10, v135, v10
	v_mul_f32_e32 v137, v11, v137
	v_mul_f32_e32 v135, 0x3fcc422a, v135
	v_fma_f32 v137, v11, v137, v11
	v_mul_f32_e32 v135, 0xbfb8aa3b, v135
	v_mul_f32_e32 v137, 0x3fcc422a, v137
	v_exp_f32_e32 v135, v135
	v_mul_f32_e32 v137, 0xbfb8aa3b, v137
	v_exp_f32_e32 v137, v137
	v_rcp_f32_e32 v141, v129
	v_add_f32_e32 v129, 1.0, v135
	global_store_dwordx2 v[142:143], v[138:139], off offset:224 sc1
	v_rcp_f32_e32 v142, v129
	v_add_f32_e32 v129, 1.0, v137
	v_rcp_f32_e32 v143, v129
	v_and_b32_e32 v135, 64, v154
	v_xor_b32_e32 v129, 1, v154
	v_add_u32_e32 v135, 64, v135
	v_cmp_lt_i32_e32 vcc, v129, v135
	ds_write_b16 v150, v138 offset:16192
	ds_write_b16_d16_hi v150, v138 offset:16336
	v_cndmask_b32_e32 v129, v154, v129, vcc
	ds_write_b16 v150, v139 offset:16480
	ds_write_b16_d16_hi v150, v139 offset:16624
	v_pk_mul_f32 v[138:139], v[8:9], v[140:141]
	v_pk_mul_f32 v[140:141], v[10:11], v[142:143]
	v_lshlrev_b32_e32 v142, 2, v129
	v_xor_b32_e32 v129, 2, v154
	v_cmp_lt_i32_e32 vcc, v129, v135
	v_cvt_pk_bf16_f32 v138, v138, v139
	v_cvt_pk_bf16_f32 v139, v140, v141
	v_cndmask_b32_e32 v129, v154, v129, vcc
	global_store_dwordx2 v[144:145], v[138:139], off offset:224 sc1
	ds_write_b16 v150, v138 offset:16224
	ds_write_b16_d16_hi v150, v138 offset:16368
	ds_write_b16 v150, v139 offset:16512
	ds_write_b16_d16_hi v150, v139 offset:16656
	v_lshlrev_b32_e32 v143, 2, v129
	v_xor_b32_e32 v129, 4, v154
	s_waitcnt lgkmcnt(0)
	v_cmp_lt_i32_e32 vcc, v129, v135
	v_mov_b32_e32 v137, v128
	v_add_u32_e32 v134, s46, v151
	v_cndmask_b32_e32 v129, v154, v129, vcc
	s_mov_b32 s47, 0
	v_lshlrev_b32_e32 v144, 2, v129
	v_lshl_add_u64 v[136:137], v[136:137], 3, s[6:7]
	s_branch .LBB0_1497

.LBB0_1497:
	v_add_u32_e32 v145, s47, v152
	s_waitcnt lgkmcnt(0)
	ds_read_b128 v[138:141], v145
	s_waitcnt lgkmcnt(0)
	v_lshlrev_b32_e32 v157, 16, v138
	v_and_b32_e32 v156, 0xffff0000, v138
	v_lshlrev_b32_e32 v138, 16, v139
	v_and_b32_e32 v158, 0xffff0000, v139
	v_pk_mul_f32 v[168:169], v[156:157], v[156:157]
	v_mul_f32_e32 v139, v138, v138
	v_mul_f32_e32 v159, v158, v158
	v_lshlrev_b32_e32 v160, 16, v140
	v_and_b32_e32 v162, 0xffff0000, v140
	v_add_f32_e32 v166, v157, v156
	v_mov_b32_e32 v167, v169
	v_mul_f32_e32 v129, v156, v156
	v_mul_f32_e32 v161, v160, v160
	v_mul_f32_e32 v163, v162, v162
	v_lshlrev_b32_e32 v140, 16, v141
	v_and_b32_e32 v164, 0xffff0000, v141
	v_pk_add_f32 v[156:157], v[166:167], v[128:129]
	v_pk_add_f32 v[138:139], v[138:139], v[158:159]
	v_mul_f32_e32 v141, v140, v140
	v_mul_f32_e32 v165, v164, v164
	v_pk_add_f32 v[138:139], v[156:157], v[138:139]
	v_pk_add_f32 v[156:157], v[160:161], v[162:163]
	v_pk_add_f32 v[140:141], v[140:141], v[164:165]
	v_pk_add_f32 v[138:139], v[138:139], v[156:157]
	s_nop 0
	v_pk_add_f32 v[138:139], v[138:139], v[140:141]
	ds_bpermute_b32 v140, v142, v138
	ds_bpermute_b32 v141, v142, v139
	s_waitcnt lgkmcnt(0)
	v_pk_add_f32 v[138:139], v[138:139], v[140:141]
	ds_bpermute_b32 v140, v143, v138
	ds_bpermute_b32 v141, v143, v139
	s_waitcnt lgkmcnt(0)
	v_pk_add_f32 v[138:139], v[138:139], v[140:141]
	ds_bpermute_b32 v140, v144, v138
	ds_bpermute_b32 v141, v144, v139
	s_and_saveexec_b64 s[44:45], s[0:1]
	s_cbranch_execz .LBB0_1499
	v_ashrrev_i32_e32 v135, 31, v134
	v_lshlrev_b64 v[156:157], 8, v[134:135]
	v_lshl_add_u64 v[156:157], v[136:137], 0, v[156:157]
	s_waitcnt lgkmcnt(0)
	v_pk_add_f32 v[138:139], v[138:139], v[140:141]
	global_store_dwordx2 v[156:157], v[138:139], off sc1
.LBB0_1499:
	s_or_b64 exec, exec, s[44:45]
	s_waitcnt lgkmcnt(0)
	ds_read_b128 v[138:141], v145 offset:1152
	s_waitcnt lgkmcnt(0)
	v_lshlrev_b32_e32 v157, 16, v138
	v_and_b32_e32 v156, 0xffff0000, v138
	v_lshlrev_b32_e32 v138, 16, v139
	v_and_b32_e32 v158, 0xffff0000, v139
	v_pk_mul_f32 v[168:169], v[156:157], v[156:157]
	v_mul_f32_e32 v139, v138, v138
	v_mul_f32_e32 v159, v158, v158
	v_lshlrev_b32_e32 v160, 16, v140
	v_and_b32_e32 v162, 0xffff0000, v140
	v_add_f32_e32 v166, v157, v156
	v_mov_b32_e32 v167, v169
	v_mul_f32_e32 v129, v156, v156
	v_mul_f32_e32 v161, v160, v160
	v_mul_f32_e32 v163, v162, v162
	v_lshlrev_b32_e32 v140, 16, v141
	v_and_b32_e32 v164, 0xffff0000, v141
	v_pk_add_f32 v[156:157], v[166:167], v[128:129]
	v_pk_add_f32 v[138:139], v[138:139], v[158:159]
	v_mul_f32_e32 v141, v140, v140
	v_mul_f32_e32 v165, v164, v164
	v_pk_add_f32 v[138:139], v[156:157], v[138:139]
	v_pk_add_f32 v[156:157], v[160:161], v[162:163]
	v_pk_add_f32 v[140:141], v[140:141], v[164:165]
	v_pk_add_f32 v[138:139], v[138:139], v[156:157]
	s_nop 0
	v_pk_add_f32 v[138:139], v[138:139], v[140:141]
	ds_bpermute_b32 v140, v142, v138
	ds_bpermute_b32 v141, v142, v139
	s_waitcnt lgkmcnt(0)
	v_pk_add_f32 v[138:139], v[138:139], v[140:141]
	ds_bpermute_b32 v140, v143, v138
	ds_bpermute_b32 v141, v143, v139
	s_waitcnt lgkmcnt(0)
	v_pk_add_f32 v[138:139], v[138:139], v[140:141]
	ds_bpermute_b32 v140, v144, v138
	ds_bpermute_b32 v141, v144, v139
	s_and_saveexec_b64 s[44:45], s[0:1]
	s_cbranch_execz .LBB0_1496
	v_add_u32_e32 v156, 8, v134
	v_ashrrev_i32_e32 v157, 31, v156
	v_lshlrev_b64 v[156:157], 8, v[156:157]
	v_lshl_add_u64 v[156:157], v[136:137], 0, v[156:157]
	s_waitcnt lgkmcnt(0)
	v_pk_add_f32 v[138:139], v[138:139], v[140:141]
	global_store_dwordx2 v[156:157], v[138:139], off sc1
	s_branch .LBB0_1496
